# GEMM tiles: first K-loop trip peeled, accumulators start from SrcC=0 instead of 128 v_mov zeroing per tile (in-proj, gate-up, down, out)
# speedup vs baseline: 1.0120x; 1.0120x over previous
; #define PG8_STAGE(bufoff, gbase, voff) do { _Pragma("unroll") for (int _i = 0; _i < 2; ++_i) \
;         __builtin_amdgcn_global_load_lds((const unsigned*)((const char*)(gbase) + (voff)[_i]), (PG8_LAS unsigned*)(lds + (bufoff) + ldsw + _i * 8192), 16, 0, 0); } while (0)
; #define PG8_LDA(dst, b, h) do { _Pragma("unroll") for (int m = 0; m < 4; ++m) _Pragma("unroll") for (int k = 0; k < 2; ++k) dst[m][k] = *(const PG8_LAS bf16x8*)(lds + PG8_SA(b, h) + aoff + m * 2048 + k * 1024); } while (0)
; #define PG8_LDB(dst, b, h) do { _Pragma("unroll") for (int n = 0; n < 2; ++n) _Pragma("unroll") for (int k = 0; k < 2; ++k) dst[n][k] = *(const PG8_LAS bf16x8*)(lds + PG8_SB(b, h) + boff + n * 2048 + k * 1024); } while (0)
; #define PG8_MMA(ai, bj, At, Bt) do { __builtin_amdgcn_s_setprio(1); _Pragma("unroll") for (int m = 0; m < 4; ++m) _Pragma("unroll") for (int n = 0; n < 2; ++n) _Pragma("unroll") for (int k = 0; k < 2; ++k) \
;         acc[ai][bj][m][n] = __builtin_amdgcn_mfma_f32_16x16x32_bf16(Bt[n][k], At[m][k], acc[ai][bj][m][n], 0, 0, 0); __builtin_amdgcn_s_setprio(0); } while (0)
; #define PG8_WAIT_V(n) asm volatile("s_waitcnt vmcnt(" #n ")" ::: "memory")
; #define PG8_WAIT_L(n) asm volatile("s_waitcnt lgkmcnt(" #n ")" ::: "memory")
; #define PG8_BAR __builtin_amdgcn_s_barrier()
; template <class Epi, class Sched, bool ALIGN_EPI = false, bool SP2 = false>
; __device__ __forceinline__ void gemm_phase(PG8_LAS unsigned char* lds, const Gemm g, const Sched& S, const Epi& E) {
;     ...
;     f32x4 acc[2][2][4][2];
; #pragma unroll
;     for (int a = 0; a < 2; ++a)
; #pragma unroll
;         for (int b = 0; b < 2; ++b)
; #pragma unroll
;             for (int m = 0; m < 4; ++m)
; #pragma unroll
;                 for (int n = 0; n < 2; ++n) acc[a][b][m][n] = (f32x4){0.f, 0.f, 0.f, 0.f};
;     ...
;             if constexpr (SP2) {
;             PG8_LDB(B0, 0, 0); PG8_LDB(B1, 0, 1); PG8_SCHED; PG8_LDA(At, 0, 0); PG8_STAGE(PG8_SA(1, 1), a1 + hstepA, voffA);
;             PG8_WAIT_V(8); PG8_WAIT_L(0); PG8_BAR; PG8_MMA(0, 0, At, B0); PG8_MMA(0, 1, At, B1); PG8_BAR; PG8_SCHED;
;             PG8_LDA(At, 0, 1); PG8_STAGE(PG8_SB(0, 0), b2, voffB); PG8_STAGE(PG8_SB(0, 1), b2 + hstepB, voffB); PG8_STAGE(PG8_SA(0, 0), a2, voffA);
;             PG8_WAIT_V(8); PG8_WAIT_L(0); PG8_BAR; PG8_MMA(1, 0, At, B0); PG8_MMA(1, 1, At, B1); PG8_BAR; PG8_SCHED;
.LBB0_34:
	s_ashr_i32 s11, s10, 31
	s_lshl_b64 s[14:15], s[10:11], 15
	s_add_u32 s14, s70, s14
	s_addc_u32 s15, s71, s15
	s_and_b64 s[0:1], s[0:1], exec
	s_cselect_b32 s11, s15, s19
	s_cselect_b32 s36, s14, s18
	s_add_u32 s0, s18, 0x404000
	s_addc_u32 s1, s19, 0
	s_add_u32 s37, s16, 0x100
	s_addc_u32 s38, s17, 0
	s_mov_b32 s39, -2
	s_add_u32 s16, s0, 0x3fc000
	s_addc_u32 s17, s1, 0
	s_cmp_eq_u32 s39, 40
	s_cselect_b32 s20, s36, s16
	s_cselect_b32 s21, s11, s17
	s_cselect_b32 s18, s12, s37
	s_cselect_b32 s19, s13, s38
	s_add_u32 s16, s20, 0x400000
	s_addc_u32 s17, s21, 0
	s_add_i32 s40, 0, 0x10000
	s_add_i32 s42, 0, 0x14000
	v_add_u32_e32 v156, s40, v153
	v_add_u32_e32 v172, s42, v153
	ds_read_b128 v[140:143], v156
	ds_read_b128 v[144:147], v156 offset:1024
	ds_read_b128 v[148:151], v156 offset:2048
	ds_read_b128 v[156:159], v156 offset:3072
	ds_read_b128 v[160:163], v172
	ds_read_b128 v[164:167], v172 offset:1024
	ds_read_b128 v[168:171], v172 offset:2048
	ds_read_b128 v[172:175], v172 offset:3072
	v_lshl_add_u64 v[192:193], s[0:1], 0, v[136:137]
	s_add_i32 m0, s23, 0xc000
	ds_read_b128 v[176:179], v155
	ds_read_b128 v[180:183], v155 offset:1024
	ds_read_b128 v[184:187], v155 offset:2048
	ds_read_b128 v[188:191], v155 offset:3072
	ds_read_b128 v[206:209], v155 offset:4096
	ds_read_b128 v[210:213], v155 offset:5120
	ds_read_b128 v[214:217], v155 offset:6144
	ds_read_b128 v[218:221], v155 offset:7168
	global_load_lds_dwordx4 v[192:193], off
	v_lshl_add_u64 v[192:193], s[0:1], 0, v[138:139]
	s_add_i32 m0, s23, 0xe000
	s_nop 0
	global_load_lds_dwordx4 v[192:193], off
	s_waitcnt vmcnt(8)
	s_waitcnt lgkmcnt(0)
	s_barrier
	s_setprio 1
	s_waitcnt lgkmcnt(0)
	v_mfma_f32_16x16x32_bf16 v[126:129], v[140:143], v[176:179], 0
	v_mfma_f32_16x16x32_bf16 v[122:125], v[148:151], v[176:179], 0
	v_mfma_f32_16x16x32_bf16 v[118:121], v[140:143], v[184:187], 0
	v_mfma_f32_16x16x32_bf16 v[114:117], v[148:151], v[184:187], 0
	v_mfma_f32_16x16x32_bf16 v[106:109], v[140:143], v[206:209], 0
	v_mfma_f32_16x16x32_bf16 v[98:101], v[148:151], v[206:209], 0
	v_mfma_f32_16x16x32_bf16 v[90:93], v[140:143], v[214:217], 0
	v_mfma_f32_16x16x32_bf16 v[82:85], v[148:151], v[214:217], 0
	v_mfma_f32_16x16x32_bf16 v[126:129], v[144:147], v[180:183], v[126:129]
	v_mfma_f32_16x16x32_bf16 v[122:125], v[156:159], v[180:183], v[122:125]
	v_mfma_f32_16x16x32_bf16 v[118:121], v[144:147], v[188:191], v[118:121]
	v_mfma_f32_16x16x32_bf16 v[114:117], v[156:159], v[188:191], v[114:117]
	v_mfma_f32_16x16x32_bf16 v[106:109], v[144:147], v[210:213], v[106:109]
	v_mfma_f32_16x16x32_bf16 v[98:101], v[156:159], v[210:213], v[98:101]
	v_mfma_f32_16x16x32_bf16 v[90:93], v[144:147], v[218:221], v[90:93]
	v_mfma_f32_16x16x32_bf16 v[82:85], v[156:159], v[218:221], v[82:85]
	s_setprio 0
	s_setprio 1
	v_mfma_f32_16x16x32_bf16 v[110:113], v[160:163], v[176:179], 0
	v_mfma_f32_16x16x32_bf16 v[102:105], v[168:171], v[176:179], 0
	v_mfma_f32_16x16x32_bf16 v[94:97], v[160:163], v[184:187], 0
	v_mfma_f32_16x16x32_bf16 v[86:89], v[168:171], v[184:187], 0
	v_mfma_f32_16x16x32_bf16 v[78:81], v[160:163], v[206:209], 0
	v_mfma_f32_16x16x32_bf16 v[74:77], v[168:171], v[206:209], 0
	v_mfma_f32_16x16x32_bf16 v[70:73], v[160:163], v[214:217], 0
	v_mfma_f32_16x16x32_bf16 v[66:69], v[168:171], v[214:217], 0
	v_mfma_f32_16x16x32_bf16 v[110:113], v[164:167], v[180:183], v[110:113]
	v_mfma_f32_16x16x32_bf16 v[102:105], v[172:175], v[180:183], v[102:105]
	v_mfma_f32_16x16x32_bf16 v[94:97], v[164:167], v[188:191], v[94:97]
	v_mfma_f32_16x16x32_bf16 v[86:89], v[172:175], v[188:191], v[86:89]
	v_mfma_f32_16x16x32_bf16 v[78:81], v[164:167], v[210:213], v[78:81]
	v_mfma_f32_16x16x32_bf16 v[74:77], v[172:175], v[210:213], v[74:77]
	v_mfma_f32_16x16x32_bf16 v[70:73], v[164:167], v[218:221], v[70:73]
	v_mfma_f32_16x16x32_bf16 v[66:69], v[172:175], v[218:221], v[66:69]
	s_setprio 0
	s_barrier
	s_add_i32 s40, s40, s22
	v_lshl_add_u64 v[192:193], s[18:19], 0, v[0:1]
	s_mov_b32 m0, s40
	ds_read_b128 v[176:179], v155 offset:16384
	ds_read_b128 v[180:183], v155 offset:17408
	ds_read_b128 v[184:187], v155 offset:18432
	ds_read_b128 v[188:191], v155 offset:19456
	ds_read_b128 v[206:209], v155 offset:20480
	ds_read_b128 v[210:213], v155 offset:21504
	ds_read_b128 v[214:217], v155 offset:22528
	ds_read_b128 v[218:221], v155 offset:23552
	global_load_lds_dwordx4 v[192:193], off
	s_add_i32 m0, s40, 0x2000
	s_add_u32 s40, s18, 0xb0000
	v_lshl_add_u64 v[222:223], s[18:19], 0, v[130:131]
	s_addc_u32 s41, s19, 0
	s_add_i32 s42, s42, s22
	global_load_lds_dwordx4 v[222:223], off
	v_lshl_add_u64 v[224:225], s[40:41], 0, v[0:1]
	s_mov_b32 m0, s42
	s_nop 0
	global_load_lds_dwordx4 v[224:225], off
	v_lshl_add_u64 v[224:225], s[40:41], 0, v[130:131]
	s_add_i32 m0, s42, 0x2000
	s_nop 0
	global_load_lds_dwordx4 v[224:225], off
	v_lshl_add_u64 v[224:225], s[20:21], 0, v[134:135]
	s_mov_b32 m0, s23
	s_nop 0
	global_load_lds_dwordx4 v[224:225], off
	v_lshl_add_u64 v[224:225], s[20:21], 0, v[132:133]
	s_mov_b32 m0, s25
	s_nop 0
	global_load_lds_dwordx4 v[224:225], off
	s_waitcnt vmcnt(8)
	s_waitcnt lgkmcnt(0)
	s_barrier
; #define PG8_STAGE(bufoff, gbase, voff) do { _Pragma("unroll") for (int _i = 0; _i < 2; ++_i) \
;         __builtin_amdgcn_global_load_lds((const unsigned*)((const char*)(gbase) + (voff)[_i]), (PG8_LAS unsigned*)(lds + (bufoff) + ldsw + _i * 8192), 16, 0, 0); } while (0)
; #define PG8_LDA(dst, b, h) do { _Pragma("unroll") for (int m = 0; m < 4; ++m) _Pragma("unroll") for (int k = 0; k < 2; ++k) dst[m][k] = *(const PG8_LAS bf16x8*)(lds + PG8_SA(b, h) + aoff + m * 2048 + k * 1024); } while (0)
; #define PG8_LDB(dst, b, h) do { _Pragma("unroll") for (int n = 0; n < 2; ++n) _Pragma("unroll") for (int k = 0; k < 2; ++k) dst[n][k] = *(const PG8_LAS bf16x8*)(lds + PG8_SB(b, h) + boff + n * 2048 + k * 1024); } while (0)
; #define PG8_MMA(ai, bj, At, Bt) do { __builtin_amdgcn_s_setprio(1); _Pragma("unroll") for (int m = 0; m < 4; ++m) _Pragma("unroll") for (int n = 0; n < 2; ++n) _Pragma("unroll") for (int k = 0; k < 2; ++k) \
;         acc[ai][bj][m][n] = __builtin_amdgcn_mfma_f32_16x16x32_bf16(Bt[n][k], At[m][k], acc[ai][bj][m][n], 0, 0, 0); __builtin_amdgcn_s_setprio(0); } while (0)
; #define PG8_WAIT_V(n) asm volatile("s_waitcnt vmcnt(" #n ")" ::: "memory")
; #define PG8_WAIT_L(n) asm volatile("s_waitcnt lgkmcnt(" #n ")" ::: "memory")
; #define PG8_BAR __builtin_amdgcn_s_barrier()
; #define PG8_SCHED __builtin_amdgcn_sched_barrier(0)
; template <class Epi, class Sched, bool ALIGN_EPI = false, bool SP2 = false>
; __device__ __forceinline__ void gemm_phase(PG8_LAS unsigned char* lds, const Gemm g, const Sched& S, const Epi& E) {
;     ...
;             PG8_WAIT_V(8); PG8_WAIT_L(0); PG8_BAR; PG8_MMA(0, 0, At, B0); PG8_MMA(0, 1, At, B1); PG8_BAR; PG8_SCHED;
;             PG8_LDA(At, 0, 1); PG8_STAGE(PG8_SB(0, 0), b2, voffB); PG8_STAGE(PG8_SB(0, 1), b2 + hstepB, voffB); PG8_STAGE(PG8_SA(0, 0), a2, voffA);
;             PG8_WAIT_V(8); PG8_WAIT_L(0); PG8_BAR; PG8_MMA(1, 0, At, B0); PG8_MMA(1, 1, At, B1); PG8_BAR; PG8_SCHED;
;             PG8_LDB(B0, 1, 0); PG8_LDB(B1, 1, 1); PG8_SCHED; PG8_LDA(At, 1, 0); PG8_STAGE(PG8_SA(0, 1), a2 + hstepA, voffA);
;             PG8_WAIT_V(8); PG8_WAIT_L(0); PG8_BAR; PG8_MMA(0, 0, At, B0); PG8_MMA(0, 1, At, B1); PG8_BAR; PG8_SCHED;
	s_setprio 1
	s_waitcnt lgkmcnt(0)
	v_mfma_f32_16x16x32_bf16 v[62:65], v[140:143], v[176:179], 0
	v_mfma_f32_16x16x32_bf16 v[58:61], v[148:151], v[176:179], 0
	v_mfma_f32_16x16x32_bf16 v[54:57], v[140:143], v[184:187], 0
	v_mfma_f32_16x16x32_bf16 v[46:49], v[148:151], v[184:187], 0
	v_mfma_f32_16x16x32_bf16 v[38:41], v[140:143], v[206:209], 0
	v_mfma_f32_16x16x32_bf16 v[30:33], v[148:151], v[206:209], 0
	v_mfma_f32_16x16x32_bf16 v[22:25], v[140:143], v[214:217], 0
	v_mfma_f32_16x16x32_bf16 v[14:17], v[148:151], v[214:217], 0
	v_mfma_f32_16x16x32_bf16 v[62:65], v[144:147], v[180:183], v[62:65]
	v_mfma_f32_16x16x32_bf16 v[58:61], v[156:159], v[180:183], v[58:61]
	v_mfma_f32_16x16x32_bf16 v[54:57], v[144:147], v[188:191], v[54:57]
	v_mfma_f32_16x16x32_bf16 v[46:49], v[156:159], v[188:191], v[46:49]
	v_mfma_f32_16x16x32_bf16 v[38:41], v[144:147], v[210:213], v[38:41]
	v_mfma_f32_16x16x32_bf16 v[30:33], v[156:159], v[210:213], v[30:33]
	v_mfma_f32_16x16x32_bf16 v[22:25], v[144:147], v[218:221], v[22:25]
	v_mfma_f32_16x16x32_bf16 v[14:17], v[156:159], v[218:221], v[14:17]
	s_setprio 0
	s_setprio 1
	v_mfma_f32_16x16x32_bf16 v[50:53], v[160:163], v[176:179], 0
	v_mfma_f32_16x16x32_bf16 v[42:45], v[168:171], v[176:179], 0
	v_mfma_f32_16x16x32_bf16 v[34:37], v[160:163], v[184:187], 0
	v_mfma_f32_16x16x32_bf16 v[26:29], v[168:171], v[184:187], 0
	v_mfma_f32_16x16x32_bf16 v[18:21], v[160:163], v[206:209], 0
	v_mfma_f32_16x16x32_bf16 v[10:13], v[168:171], v[206:209], 0
	v_mfma_f32_16x16x32_bf16 v[6:9], v[160:163], v[214:217], 0
	v_mfma_f32_16x16x32_bf16 v[2:5], v[168:171], v[214:217], 0
	v_mfma_f32_16x16x32_bf16 v[50:53], v[164:167], v[180:183], v[50:53]
	v_mfma_f32_16x16x32_bf16 v[42:45], v[172:175], v[180:183], v[42:45]
	v_mfma_f32_16x16x32_bf16 v[34:37], v[164:167], v[188:191], v[34:37]
	v_mfma_f32_16x16x32_bf16 v[26:29], v[172:175], v[188:191], v[26:29]
	v_mfma_f32_16x16x32_bf16 v[18:21], v[164:167], v[210:213], v[18:21]
	v_mfma_f32_16x16x32_bf16 v[10:13], v[172:175], v[210:213], v[10:13]
	v_mfma_f32_16x16x32_bf16 v[6:9], v[164:167], v[218:221], v[6:9]
	v_mfma_f32_16x16x32_bf16 v[2:5], v[172:175], v[218:221], v[2:5]
	s_setprio 0
	s_barrier
	s_add_i32 s40, 0, 0x18000
	s_add_i32 s41, 0, 0x1c000
	v_add_u32_e32 v156, s40, v153
	v_add_u32_e32 v172, s41, v153
	ds_read_b128 v[140:143], v156
	ds_read_b128 v[144:147], v156 offset:1024
	ds_read_b128 v[148:151], v156 offset:2048
	ds_read_b128 v[156:159], v156 offset:3072
	ds_read_b128 v[160:163], v172
	ds_read_b128 v[164:167], v172 offset:1024
	ds_read_b128 v[168:171], v172 offset:2048
	ds_read_b128 v[172:175], v172 offset:3072
	s_add_u32 s20, s20, 0x4000
	s_addc_u32 s21, s21, 0
	s_mov_b32 m0, s26
	v_lshl_add_u64 v[224:225], s[20:21], 0, v[134:135]
	ds_read_b128 v[176:179], v155 offset:32768
	ds_read_b128 v[180:183], v155 offset:33792
	ds_read_b128 v[184:187], v155 offset:34816
	ds_read_b128 v[188:191], v155 offset:35840
	ds_read_b128 v[206:209], v155 offset:36864
	ds_read_b128 v[210:213], v155 offset:37888
	ds_read_b128 v[214:217], v155 offset:38912
	ds_read_b128 v[218:221], v155 offset:39936
	global_load_lds_dwordx4 v[224:225], off
	v_lshl_add_u64 v[224:225], s[20:21], 0, v[132:133]
	s_mov_b32 m0, s27
	s_nop 0
	global_load_lds_dwordx4 v[224:225], off
	s_waitcnt vmcnt(8)
	s_waitcnt lgkmcnt(0)
	s_barrier
	s_setprio 1
	s_waitcnt lgkmcnt(0)
	v_mfma_f32_16x16x32_bf16 v[126:129], v[140:143], v[176:179], v[126:129]
	v_mfma_f32_16x16x32_bf16 v[122:125], v[148:151], v[176:179], v[122:125]
	v_mfma_f32_16x16x32_bf16 v[118:121], v[140:143], v[184:187], v[118:121]
	v_mfma_f32_16x16x32_bf16 v[114:117], v[148:151], v[184:187], v[114:117]
	v_mfma_f32_16x16x32_bf16 v[106:109], v[140:143], v[206:209], v[106:109]
	v_mfma_f32_16x16x32_bf16 v[98:101], v[148:151], v[206:209], v[98:101]
	v_mfma_f32_16x16x32_bf16 v[90:93], v[140:143], v[214:217], v[90:93]
	v_mfma_f32_16x16x32_bf16 v[82:85], v[148:151], v[214:217], v[82:85]
	v_mfma_f32_16x16x32_bf16 v[126:129], v[144:147], v[180:183], v[126:129]
	v_mfma_f32_16x16x32_bf16 v[122:125], v[156:159], v[180:183], v[122:125]
	v_mfma_f32_16x16x32_bf16 v[118:121], v[144:147], v[188:191], v[118:121]
	v_mfma_f32_16x16x32_bf16 v[114:117], v[156:159], v[188:191], v[114:117]
	v_mfma_f32_16x16x32_bf16 v[106:109], v[144:147], v[210:213], v[106:109]
	v_mfma_f32_16x16x32_bf16 v[98:101], v[156:159], v[210:213], v[98:101]
	v_mfma_f32_16x16x32_bf16 v[90:93], v[144:147], v[218:221], v[90:93]
	v_mfma_f32_16x16x32_bf16 v[82:85], v[156:159], v[218:221], v[82:85]
	s_setprio 0
	s_setprio 1
	v_mfma_f32_16x16x32_bf16 v[110:113], v[160:163], v[176:179], v[110:113]
	v_mfma_f32_16x16x32_bf16 v[102:105], v[168:171], v[176:179], v[102:105]
	v_mfma_f32_16x16x32_bf16 v[94:97], v[160:163], v[184:187], v[94:97]
	v_mfma_f32_16x16x32_bf16 v[86:89], v[168:171], v[184:187], v[86:89]
	v_mfma_f32_16x16x32_bf16 v[78:81], v[160:163], v[206:209], v[78:81]
	v_mfma_f32_16x16x32_bf16 v[74:77], v[168:171], v[206:209], v[74:77]
	v_mfma_f32_16x16x32_bf16 v[70:73], v[160:163], v[214:217], v[70:73]
	v_mfma_f32_16x16x32_bf16 v[66:69], v[168:171], v[214:217], v[66:69]
	v_mfma_f32_16x16x32_bf16 v[110:113], v[164:167], v[180:183], v[110:113]
	v_mfma_f32_16x16x32_bf16 v[102:105], v[172:175], v[180:183], v[102:105]
	v_mfma_f32_16x16x32_bf16 v[94:97], v[164:167], v[188:191], v[94:97]
	v_mfma_f32_16x16x32_bf16 v[86:89], v[172:175], v[188:191], v[86:89]
	v_mfma_f32_16x16x32_bf16 v[78:81], v[164:167], v[210:213], v[78:81]
	v_mfma_f32_16x16x32_bf16 v[74:77], v[172:175], v[210:213], v[74:77]
	v_mfma_f32_16x16x32_bf16 v[70:73], v[164:167], v[218:221], v[70:73]
	v_mfma_f32_16x16x32_bf16 v[66:69], v[172:175], v[218:221], v[66:69]
	s_setprio 0
	s_barrier
; #define PG8_STAGE(bufoff, gbase, voff) do { _Pragma("unroll") for (int _i = 0; _i < 2; ++_i) \
;         __builtin_amdgcn_global_load_lds((const unsigned*)((const char*)(gbase) + (voff)[_i]), (PG8_LAS unsigned*)(lds + (bufoff) + ldsw + _i * 8192), 16, 0, 0); } while (0)
; #define PG8_LDA(dst, b, h) do { _Pragma("unroll") for (int m = 0; m < 4; ++m) _Pragma("unroll") for (int k = 0; k < 2; ++k) dst[m][k] = *(const PG8_LAS bf16x8*)(lds + PG8_SA(b, h) + aoff + m * 2048 + k * 1024); } while (0)
; #define PG8_MMA(ai, bj, At, Bt) do { __builtin_amdgcn_s_setprio(1); _Pragma("unroll") for (int m = 0; m < 4; ++m) _Pragma("unroll") for (int n = 0; n < 2; ++n) _Pragma("unroll") for (int k = 0; k < 2; ++k) \
;         acc[ai][bj][m][n] = __builtin_amdgcn_mfma_f32_16x16x32_bf16(Bt[n][k], At[m][k], acc[ai][bj][m][n], 0, 0, 0); __builtin_amdgcn_s_setprio(0); } while (0)
; #define PG8_WAIT_V(n) asm volatile("s_waitcnt vmcnt(" #n ")" ::: "memory")
; #define PG8_WAIT_L(n) asm volatile("s_waitcnt lgkmcnt(" #n ")" ::: "memory")
; #define PG8_BAR __builtin_amdgcn_s_barrier()
; #define PG8_SCHED __builtin_amdgcn_sched_barrier(0)
; template <class Epi, class Sched, bool ALIGN_EPI = false, bool SP2 = false>
; __device__ __forceinline__ void gemm_phase(PG8_LAS unsigned char* lds, const Gemm g, const Sched& S, const Epi& E) {
;     ...
;             PG8_LDA(At, 1, 1); PG8_STAGE(PG8_SB(1, 0), b3, voffB); PG8_STAGE(PG8_SB(1, 1), b3 + hstepB, voffB); PG8_STAGE(PG8_SA(1, 0), a3, voffA);
;             PG8_WAIT_V(8); PG8_WAIT_L(0); PG8_BAR; PG8_MMA(1, 0, At, B0); PG8_MMA(1, 1, At, B1); PG8_BAR; PG8_SCHED;
	s_add_i32 s20, s40, s22
	v_lshl_add_u64 v[192:193], v[192:193], 0, s[78:79]
	s_mov_b32 m0, s20
	ds_read_b128 v[176:179], v155 offset:49152
	ds_read_b128 v[180:183], v155 offset:50176
	ds_read_b128 v[184:187], v155 offset:51200
	ds_read_b128 v[188:191], v155 offset:52224
	ds_read_b128 v[206:209], v155 offset:53248
	ds_read_b128 v[210:213], v155 offset:54272
	ds_read_b128 v[214:217], v155 offset:55296
	ds_read_b128 v[218:221], v155 offset:56320
	global_load_lds_dwordx4 v[192:193], off
	s_add_i32 m0, s20, 0x2000
	s_add_u32 s18, s18, 0xb0080
	v_lshl_add_u64 v[192:193], v[222:223], 0, s[78:79]
	s_addc_u32 s19, s19, 0
	s_add_i32 s20, s41, s22
	global_load_lds_dwordx4 v[192:193], off
	v_lshl_add_u64 v[192:193], s[18:19], 0, v[0:1]
	s_mov_b32 m0, s20
	s_nop 0
	global_load_lds_dwordx4 v[192:193], off
	v_lshl_add_u64 v[192:193], s[18:19], 0, v[130:131]
	s_add_i32 m0, s20, 0x2000
	s_nop 0
	global_load_lds_dwordx4 v[192:193], off
	v_lshl_add_u64 v[192:193], s[16:17], 0, v[134:135]
	s_mov_b32 m0, s28
	s_nop 0
	global_load_lds_dwordx4 v[192:193], off
	v_lshl_add_u64 v[192:193], s[16:17], 0, v[132:133]
	s_mov_b32 m0, s29
	s_nop 0
	global_load_lds_dwordx4 v[192:193], off
	s_waitcnt vmcnt(8)
	s_waitcnt lgkmcnt(0)
	s_barrier
	s_setprio 1
	s_waitcnt lgkmcnt(0)
	v_mfma_f32_16x16x32_bf16 v[62:65], v[140:143], v[176:179], v[62:65]
	v_mfma_f32_16x16x32_bf16 v[58:61], v[148:151], v[176:179], v[58:61]
	v_mfma_f32_16x16x32_bf16 v[54:57], v[140:143], v[184:187], v[54:57]
	v_mfma_f32_16x16x32_bf16 v[46:49], v[148:151], v[184:187], v[46:49]
	v_mfma_f32_16x16x32_bf16 v[38:41], v[140:143], v[206:209], v[38:41]
	v_mfma_f32_16x16x32_bf16 v[30:33], v[148:151], v[206:209], v[30:33]
	v_mfma_f32_16x16x32_bf16 v[22:25], v[140:143], v[214:217], v[22:25]
	v_mfma_f32_16x16x32_bf16 v[14:17], v[148:151], v[214:217], v[14:17]
	v_mfma_f32_16x16x32_bf16 v[62:65], v[144:147], v[180:183], v[62:65]
	v_mfma_f32_16x16x32_bf16 v[58:61], v[156:159], v[180:183], v[58:61]
	v_mfma_f32_16x16x32_bf16 v[54:57], v[144:147], v[188:191], v[54:57]
	v_mfma_f32_16x16x32_bf16 v[46:49], v[156:159], v[188:191], v[46:49]
	v_mfma_f32_16x16x32_bf16 v[38:41], v[144:147], v[210:213], v[38:41]
	v_mfma_f32_16x16x32_bf16 v[30:33], v[156:159], v[210:213], v[30:33]
	v_mfma_f32_16x16x32_bf16 v[22:25], v[144:147], v[218:221], v[22:25]
	v_mfma_f32_16x16x32_bf16 v[14:17], v[156:159], v[218:221], v[14:17]
	s_setprio 0
	s_setprio 1
	v_mfma_f32_16x16x32_bf16 v[50:53], v[160:163], v[176:179], v[50:53]
	v_mfma_f32_16x16x32_bf16 v[42:45], v[168:171], v[176:179], v[42:45]
	v_mfma_f32_16x16x32_bf16 v[34:37], v[160:163], v[184:187], v[34:37]
	v_mfma_f32_16x16x32_bf16 v[26:29], v[168:171], v[184:187], v[26:29]
	v_mfma_f32_16x16x32_bf16 v[18:21], v[160:163], v[206:209], v[18:21]
	v_mfma_f32_16x16x32_bf16 v[10:13], v[168:171], v[206:209], v[10:13]
	v_mfma_f32_16x16x32_bf16 v[6:9], v[160:163], v[214:217], v[6:9]
	v_mfma_f32_16x16x32_bf16 v[2:5], v[168:171], v[214:217], v[2:5]
	v_mfma_f32_16x16x32_bf16 v[50:53], v[164:167], v[180:183], v[50:53]
	v_mfma_f32_16x16x32_bf16 v[42:45], v[172:175], v[180:183], v[42:45]
	v_mfma_f32_16x16x32_bf16 v[34:37], v[164:167], v[188:191], v[34:37]
	v_mfma_f32_16x16x32_bf16 v[26:29], v[172:175], v[188:191], v[26:29]
	v_mfma_f32_16x16x32_bf16 v[18:21], v[164:167], v[210:213], v[18:21]
	v_mfma_f32_16x16x32_bf16 v[10:13], v[172:175], v[210:213], v[10:13]
	v_mfma_f32_16x16x32_bf16 v[6:9], v[164:167], v[218:221], v[6:9]
	v_mfma_f32_16x16x32_bf16 v[2:5], v[172:175], v[218:221], v[2:5]
	s_setprio 0
	s_barrier
	s_add_i32 s39, s39, 2
	s_add_u32 s0, s0, 0x800000
	s_addc_u32 s1, s1, 0
	s_add_u32 s37, s37, 0x100
	s_addc_u32 s38, s38, 0

; #define PG8_STAGE(bufoff, gbase, voff) do { _Pragma("unroll") for (int _i = 0; _i < 2; ++_i) \
;         __builtin_amdgcn_global_load_lds((const unsigned*)((const char*)(gbase) + (voff)[_i]), (PG8_LAS unsigned*)(lds + (bufoff) + ldsw + _i * 8192), 16, 0, 0); } while (0)
; #define PG8_LDA(dst, b, h) do { _Pragma("unroll") for (int m = 0; m < 4; ++m) _Pragma("unroll") for (int k = 0; k < 2; ++k) dst[m][k] = *(const PG8_LAS bf16x8*)(lds + PG8_SA(b, h) + aoff + m * 2048 + k * 1024); } while (0)
; #define PG8_LDB(dst, b, h) do { _Pragma("unroll") for (int n = 0; n < 2; ++n) _Pragma("unroll") for (int k = 0; k < 2; ++k) dst[n][k] = *(const PG8_LAS bf16x8*)(lds + PG8_SB(b, h) + boff + n * 2048 + k * 1024); } while (0)
; #define PG8_MMA(ai, bj, At, Bt) do { __builtin_amdgcn_s_setprio(1); _Pragma("unroll") for (int m = 0; m < 4; ++m) _Pragma("unroll") for (int n = 0; n < 2; ++n) _Pragma("unroll") for (int k = 0; k < 2; ++k) \
;         acc[ai][bj][m][n] = __builtin_amdgcn_mfma_f32_16x16x32_bf16(Bt[n][k], At[m][k], acc[ai][bj][m][n], 0, 0, 0); __builtin_amdgcn_s_setprio(0); } while (0)
; template <class Epi, class Sched, bool ALIGN_EPI = false, bool SP2 = false>
; __device__ __forceinline__ void gemm_phase(PG8_LAS unsigned char* lds, const Gemm g, const Sched& S, const Epi& E) {
;     ...
;         const bool has_next = S.next(ui + 1, nxt);
;         const char* nA = has_next ? (const char*)g.A + (size_t)nxt.pm * tstepA + (size_t)nxt.pn * pnoffA : cA; const char* nB = has_next ? (const char*)g.Bt + (size_t)nxt.pn * tstepB : cB;
;         for (int t = 0; t < nt; t += 2) {
;             const bool last = (t == nt - 2);
;             const char* a1 = cA + (size_t)(t + 1) * kstepA;
;             const char* a2 = last ? nA : cA + (size_t)(t + 2) * kstepA; const char* b2 = last ? nB : cB + (size_t)(t + 2) * kstep;
;             const char* a3 = a2 + kstepA; const char* b3 = b2 + kstep;
;             if (last && has_next) S.a_ready(nxt);
;             if constexpr (SP2) {
;             PG8_LDB(B0, 0, 0); PG8_LDB(B1, 0, 1); PG8_SCHED; PG8_LDA(At, 0, 0); PG8_STAGE(PG8_SA(1, 1), a1 + hstepA, voffA);
;             PG8_WAIT_V(8); PG8_WAIT_L(0); PG8_BAR; PG8_MMA(0, 0, At, B0); PG8_MMA(0, 1, At, B1); PG8_BAR; PG8_SCHED;
;             PG8_LDA(At, 0, 1); PG8_STAGE(PG8_SB(0, 0), b2, voffB); PG8_STAGE(PG8_SB(0, 1), b2 + hstepB, voffB); PG8_STAGE(PG8_SA(0, 0), a2, voffA);
.LBB0_52:
	s_ashr_i32 s11, s10, 31
	s_lshl_b64 s[12:13], s[10:11], 15
	s_add_u32 s12, s72, s12
	s_addc_u32 s13, s73, s13
	s_and_b64 s[14:15], s[4:5], exec
	s_cselect_b32 s11, s13, s17
	s_cselect_b32 s38, s12, s16
	s_ashr_i32 s9, s8, 31
	s_lshl_b64 s[14:15], s[8:9], 19
	s_add_u32 s14, s66, s14
	s_addc_u32 s15, s67, s15
	s_and_b64 s[20:21], s[4:5], exec
	s_cselect_b32 s9, s15, s19
	s_cselect_b32 s39, s14, s18
	s_add_u32 s40, s18, 0x100
	s_addc_u32 s41, s19, 0
	s_add_u32 s16, s16, 0x404000
	s_addc_u32 s17, s17, 0
	s_mov_b32 s42, -2
	s_add_u32 s18, s16, 0x3fc000
	s_addc_u32 s19, s17, 0
	s_cmp_eq_u32 s42, 12
	s_cselect_b32 s22, s38, s18
	s_cselect_b32 s23, s11, s19
	s_cselect_b32 s20, s39, s40
	s_cselect_b32 s21, s9, s41
	s_add_u32 s18, s22, 0x400000
	s_addc_u32 s19, s23, 0
	s_add_i32 s43, 0, 0x10000
	v_add_u32_e32 v149, s43, v147
	s_add_i32 s46, 0, 0x14000
	ds_read_b128 v[142:145], v149
	ds_read_b128 v[150:153], v149 offset:1024
	ds_read_b128 v[154:157], v149 offset:2048
	ds_read_b128 v[158:161], v149 offset:3072
	v_add_u32_e32 v149, s46, v147
	ds_read_b128 v[162:165], v149
	ds_read_b128 v[166:169], v149 offset:1024
	ds_read_b128 v[170:173], v149 offset:2048
	ds_read_b128 v[174:177], v149 offset:3072
	v_lshl_add_u64 v[222:223], s[16:17], 0, v[138:139]
	s_add_i32 m0, s26, 0xc000
	ds_read_b128 v[178:181], v148
	ds_read_b128 v[182:185], v148 offset:1024
	ds_read_b128 v[186:189], v148 offset:2048
	ds_read_b128 v[190:193], v148 offset:3072
	ds_read_b128 v[206:209], v148 offset:4096
	ds_read_b128 v[210:213], v148 offset:5120
	ds_read_b128 v[214:217], v148 offset:6144
	ds_read_b128 v[218:221], v148 offset:7168
	global_load_lds_dwordx4 v[222:223], off
	v_lshl_add_u64 v[222:223], s[16:17], 0, v[140:141]
	s_add_i32 m0, s26, 0xe000
	s_nop 0
	global_load_lds_dwordx4 v[222:223], off
	s_waitcnt vmcnt(8)
	s_waitcnt lgkmcnt(0)
	s_barrier
	s_setprio 1
	s_waitcnt lgkmcnt(0)
	v_mfma_f32_16x16x32_bf16 v[126:129], v[142:145], v[178:181], 0
	v_mfma_f32_16x16x32_bf16 v[122:125], v[154:157], v[178:181], 0
	v_mfma_f32_16x16x32_bf16 v[110:113], v[142:145], v[186:189], 0
	v_mfma_f32_16x16x32_bf16 v[106:109], v[154:157], v[186:189], 0
	v_mfma_f32_16x16x32_bf16 v[94:97], v[142:145], v[206:209], 0
	v_mfma_f32_16x16x32_bf16 v[90:93], v[154:157], v[206:209], 0
	v_mfma_f32_16x16x32_bf16 v[78:81], v[142:145], v[214:217], 0
	v_mfma_f32_16x16x32_bf16 v[74:77], v[154:157], v[214:217], 0
	v_mfma_f32_16x16x32_bf16 v[126:129], v[150:153], v[182:185], v[126:129]
	v_mfma_f32_16x16x32_bf16 v[122:125], v[158:161], v[182:185], v[122:125]
	v_mfma_f32_16x16x32_bf16 v[110:113], v[150:153], v[190:193], v[110:113]
	v_mfma_f32_16x16x32_bf16 v[106:109], v[158:161], v[190:193], v[106:109]
	v_mfma_f32_16x16x32_bf16 v[94:97], v[150:153], v[210:213], v[94:97]
	v_mfma_f32_16x16x32_bf16 v[90:93], v[158:161], v[210:213], v[90:93]
	v_mfma_f32_16x16x32_bf16 v[78:81], v[150:153], v[218:221], v[78:81]
	v_mfma_f32_16x16x32_bf16 v[74:77], v[158:161], v[218:221], v[74:77]
	s_setprio 0
	s_setprio 1
	v_mfma_f32_16x16x32_bf16 v[118:121], v[162:165], v[178:181], 0
	v_mfma_f32_16x16x32_bf16 v[114:117], v[170:173], v[178:181], 0
	v_mfma_f32_16x16x32_bf16 v[102:105], v[162:165], v[186:189], 0
	v_mfma_f32_16x16x32_bf16 v[98:101], v[170:173], v[186:189], 0
	v_mfma_f32_16x16x32_bf16 v[86:89], v[162:165], v[206:209], 0
	v_mfma_f32_16x16x32_bf16 v[82:85], v[170:173], v[206:209], 0
	v_mfma_f32_16x16x32_bf16 v[70:73], v[162:165], v[214:217], 0
	v_mfma_f32_16x16x32_bf16 v[66:69], v[170:173], v[214:217], 0
	v_mfma_f32_16x16x32_bf16 v[118:121], v[166:169], v[182:185], v[118:121]
	v_mfma_f32_16x16x32_bf16 v[114:117], v[174:177], v[182:185], v[114:117]
	v_mfma_f32_16x16x32_bf16 v[102:105], v[166:169], v[190:193], v[102:105]
	v_mfma_f32_16x16x32_bf16 v[98:101], v[174:177], v[190:193], v[98:101]
	v_mfma_f32_16x16x32_bf16 v[86:89], v[166:169], v[210:213], v[86:89]
	v_mfma_f32_16x16x32_bf16 v[82:85], v[174:177], v[210:213], v[82:85]
	v_mfma_f32_16x16x32_bf16 v[70:73], v[166:169], v[218:221], v[70:73]
	v_mfma_f32_16x16x32_bf16 v[66:69], v[174:177], v[218:221], v[66:69]
	s_setprio 0
	s_barrier
	s_add_i32 s43, s43, s25
	v_lshl_add_u64 v[222:223], s[20:21], 0, v[0:1]
	s_mov_b32 m0, s43
	ds_read_b128 v[178:181], v148 offset:16384
	ds_read_b128 v[182:185], v148 offset:17408
	ds_read_b128 v[186:189], v148 offset:18432
	ds_read_b128 v[190:193], v148 offset:19456
	ds_read_b128 v[206:209], v148 offset:20480
	ds_read_b128 v[210:213], v148 offset:21504
	ds_read_b128 v[214:217], v148 offset:22528
	ds_read_b128 v[218:221], v148 offset:23552
	global_load_lds_dwordx4 v[222:223], off
	s_add_i32 m0, s43, 0x2000
	s_add_u32 s44, s20, 0x40000
	v_lshl_add_u64 v[224:225], s[20:21], 0, v[130:131]
	s_addc_u32 s45, s21, 0
	s_add_i32 s43, s46, s25
	global_load_lds_dwordx4 v[224:225], off
	v_lshl_add_u64 v[226:227], s[44:45], 0, v[0:1]
	s_mov_b32 m0, s43
	s_nop 0
	global_load_lds_dwordx4 v[226:227], off
	v_lshl_add_u64 v[226:227], s[44:45], 0, v[130:131]
	s_add_i32 m0, s43, 0x2000
	s_nop 0
	global_load_lds_dwordx4 v[226:227], off
	v_lshl_add_u64 v[226:227], s[22:23], 0, v[134:135]
	s_mov_b32 m0, s26
	s_nop 0
	global_load_lds_dwordx4 v[226:227], off
	v_lshl_add_u64 v[226:227], s[22:23], 0, v[132:133]
	s_mov_b32 m0, s27
	s_nop 0
	global_load_lds_dwordx4 v[226:227], off
	s_waitcnt vmcnt(8)
	s_waitcnt lgkmcnt(0)
	s_barrier
; #define PG8_STAGE(bufoff, gbase, voff) do { _Pragma("unroll") for (int _i = 0; _i < 2; ++_i) \
;         __builtin_amdgcn_global_load_lds((const unsigned*)((const char*)(gbase) + (voff)[_i]), (PG8_LAS unsigned*)(lds + (bufoff) + ldsw + _i * 8192), 16, 0, 0); } while (0)
; #define PG8_LDA(dst, b, h) do { _Pragma("unroll") for (int m = 0; m < 4; ++m) _Pragma("unroll") for (int k = 0; k < 2; ++k) dst[m][k] = *(const PG8_LAS bf16x8*)(lds + PG8_SA(b, h) + aoff + m * 2048 + k * 1024); } while (0)
; #define PG8_LDB(dst, b, h) do { _Pragma("unroll") for (int n = 0; n < 2; ++n) _Pragma("unroll") for (int k = 0; k < 2; ++k) dst[n][k] = *(const PG8_LAS bf16x8*)(lds + PG8_SB(b, h) + boff + n * 2048 + k * 1024); } while (0)
; #define PG8_MMA(ai, bj, At, Bt) do { __builtin_amdgcn_s_setprio(1); _Pragma("unroll") for (int m = 0; m < 4; ++m) _Pragma("unroll") for (int n = 0; n < 2; ++n) _Pragma("unroll") for (int k = 0; k < 2; ++k) \
;         acc[ai][bj][m][n] = __builtin_amdgcn_mfma_f32_16x16x32_bf16(Bt[n][k], At[m][k], acc[ai][bj][m][n], 0, 0, 0); __builtin_amdgcn_s_setprio(0); } while (0)
; #define PG8_WAIT_V(n) asm volatile("s_waitcnt vmcnt(" #n ")" ::: "memory")
; #define PG8_WAIT_L(n) asm volatile("s_waitcnt lgkmcnt(" #n ")" ::: "memory")
; #define PG8_BAR __builtin_amdgcn_s_barrier()
; #define PG8_SCHED __builtin_amdgcn_sched_barrier(0)
; template <class Epi, class Sched, bool ALIGN_EPI = false, bool SP2 = false>
; __device__ __forceinline__ void gemm_phase(PG8_LAS unsigned char* lds, const Gemm g, const Sched& S, const Epi& E) {
;     ...
;             PG8_WAIT_V(8); PG8_WAIT_L(0); PG8_BAR; PG8_MMA(1, 0, At, B0); PG8_MMA(1, 1, At, B1); PG8_BAR; PG8_SCHED;
;             PG8_LDB(B0, 1, 0); PG8_LDB(B1, 1, 1); PG8_SCHED; PG8_LDA(At, 1, 0); PG8_STAGE(PG8_SA(0, 1), a2 + hstepA, voffA);
;             PG8_WAIT_V(8); PG8_WAIT_L(0); PG8_BAR; PG8_MMA(0, 0, At, B0); PG8_MMA(0, 1, At, B1); PG8_BAR; PG8_SCHED;
;             PG8_LDA(At, 1, 1); PG8_STAGE(PG8_SB(1, 0), b3, voffB); PG8_STAGE(PG8_SB(1, 1), b3 + hstepB, voffB); PG8_STAGE(PG8_SA(1, 0), a3, voffA);
	s_setprio 1
	s_waitcnt lgkmcnt(0)
	v_mfma_f32_16x16x32_bf16 v[62:65], v[142:145], v[178:181], 0
	v_mfma_f32_16x16x32_bf16 v[58:61], v[154:157], v[178:181], 0
	v_mfma_f32_16x16x32_bf16 v[46:49], v[142:145], v[186:189], 0
	v_mfma_f32_16x16x32_bf16 v[42:45], v[154:157], v[186:189], 0
	v_mfma_f32_16x16x32_bf16 v[30:33], v[142:145], v[206:209], 0
	v_mfma_f32_16x16x32_bf16 v[26:29], v[154:157], v[206:209], 0
	v_mfma_f32_16x16x32_bf16 v[14:17], v[142:145], v[214:217], 0
	v_mfma_f32_16x16x32_bf16 v[10:13], v[154:157], v[214:217], 0
	v_mfma_f32_16x16x32_bf16 v[62:65], v[150:153], v[182:185], v[62:65]
	v_mfma_f32_16x16x32_bf16 v[58:61], v[158:161], v[182:185], v[58:61]
	v_mfma_f32_16x16x32_bf16 v[46:49], v[150:153], v[190:193], v[46:49]
	v_mfma_f32_16x16x32_bf16 v[42:45], v[158:161], v[190:193], v[42:45]
	v_mfma_f32_16x16x32_bf16 v[30:33], v[150:153], v[210:213], v[30:33]
	v_mfma_f32_16x16x32_bf16 v[26:29], v[158:161], v[210:213], v[26:29]
	v_mfma_f32_16x16x32_bf16 v[14:17], v[150:153], v[218:221], v[14:17]
	v_mfma_f32_16x16x32_bf16 v[10:13], v[158:161], v[218:221], v[10:13]
	s_setprio 0
	s_setprio 1
	v_mfma_f32_16x16x32_bf16 v[54:57], v[162:165], v[178:181], 0
	v_mfma_f32_16x16x32_bf16 v[50:53], v[170:173], v[178:181], 0
	v_mfma_f32_16x16x32_bf16 v[38:41], v[162:165], v[186:189], 0
	v_mfma_f32_16x16x32_bf16 v[34:37], v[170:173], v[186:189], 0
	v_mfma_f32_16x16x32_bf16 v[22:25], v[162:165], v[206:209], 0
	v_mfma_f32_16x16x32_bf16 v[18:21], v[170:173], v[206:209], 0
	v_mfma_f32_16x16x32_bf16 v[6:9], v[162:165], v[214:217], 0
	v_mfma_f32_16x16x32_bf16 v[2:5], v[170:173], v[214:217], 0
	v_mfma_f32_16x16x32_bf16 v[54:57], v[166:169], v[182:185], v[54:57]
	v_mfma_f32_16x16x32_bf16 v[50:53], v[174:177], v[182:185], v[50:53]
	v_mfma_f32_16x16x32_bf16 v[38:41], v[166:169], v[190:193], v[38:41]
	v_mfma_f32_16x16x32_bf16 v[34:37], v[174:177], v[190:193], v[34:37]
	v_mfma_f32_16x16x32_bf16 v[22:25], v[166:169], v[210:213], v[22:25]
	v_mfma_f32_16x16x32_bf16 v[18:21], v[174:177], v[210:213], v[18:21]
	v_mfma_f32_16x16x32_bf16 v[6:9], v[166:169], v[218:221], v[6:9]
	v_mfma_f32_16x16x32_bf16 v[2:5], v[174:177], v[218:221], v[2:5]
	s_setprio 0
	s_barrier
	s_add_i32 s43, 0, 0x18000
	v_add_u32_e32 v149, s43, v147
	s_add_i32 s44, 0, 0x1c000
	ds_read_b128 v[142:145], v149
	ds_read_b128 v[150:153], v149 offset:1024
	ds_read_b128 v[154:157], v149 offset:2048
	ds_read_b128 v[158:161], v149 offset:3072
	v_add_u32_e32 v149, s44, v147
	ds_read_b128 v[162:165], v149
	ds_read_b128 v[166:169], v149 offset:1024
	ds_read_b128 v[170:173], v149 offset:2048
	ds_read_b128 v[174:177], v149 offset:3072
	s_add_u32 s22, s22, 0x4000
	s_addc_u32 s23, s23, 0
	s_mov_b32 m0, s28
	v_lshl_add_u64 v[226:227], s[22:23], 0, v[134:135]
	ds_read_b128 v[178:181], v148 offset:32768
	ds_read_b128 v[182:185], v148 offset:33792
	ds_read_b128 v[186:189], v148 offset:34816
	ds_read_b128 v[190:193], v148 offset:35840
	ds_read_b128 v[206:209], v148 offset:36864
	ds_read_b128 v[210:213], v148 offset:37888
	ds_read_b128 v[214:217], v148 offset:38912
	ds_read_b128 v[218:221], v148 offset:39936
	global_load_lds_dwordx4 v[226:227], off
	v_lshl_add_u64 v[226:227], s[22:23], 0, v[132:133]
	s_mov_b32 m0, s29
	s_nop 0
	global_load_lds_dwordx4 v[226:227], off
	s_waitcnt vmcnt(8)
	s_waitcnt lgkmcnt(0)
	s_barrier
	s_setprio 1
	s_waitcnt lgkmcnt(0)
	v_mfma_f32_16x16x32_bf16 v[126:129], v[142:145], v[178:181], v[126:129]
	v_mfma_f32_16x16x32_bf16 v[122:125], v[154:157], v[178:181], v[122:125]
	v_mfma_f32_16x16x32_bf16 v[110:113], v[142:145], v[186:189], v[110:113]
	v_mfma_f32_16x16x32_bf16 v[106:109], v[154:157], v[186:189], v[106:109]
	v_mfma_f32_16x16x32_bf16 v[94:97], v[142:145], v[206:209], v[94:97]
	v_mfma_f32_16x16x32_bf16 v[90:93], v[154:157], v[206:209], v[90:93]
	v_mfma_f32_16x16x32_bf16 v[78:81], v[142:145], v[214:217], v[78:81]
	v_mfma_f32_16x16x32_bf16 v[74:77], v[154:157], v[214:217], v[74:77]
	v_mfma_f32_16x16x32_bf16 v[126:129], v[150:153], v[182:185], v[126:129]
	v_mfma_f32_16x16x32_bf16 v[122:125], v[158:161], v[182:185], v[122:125]
	v_mfma_f32_16x16x32_bf16 v[110:113], v[150:153], v[190:193], v[110:113]
	v_mfma_f32_16x16x32_bf16 v[106:109], v[158:161], v[190:193], v[106:109]
	v_mfma_f32_16x16x32_bf16 v[94:97], v[150:153], v[210:213], v[94:97]
	v_mfma_f32_16x16x32_bf16 v[90:93], v[158:161], v[210:213], v[90:93]
	v_mfma_f32_16x16x32_bf16 v[78:81], v[150:153], v[218:221], v[78:81]
	v_mfma_f32_16x16x32_bf16 v[74:77], v[158:161], v[218:221], v[74:77]
	s_setprio 0
	s_setprio 1
	v_mfma_f32_16x16x32_bf16 v[118:121], v[162:165], v[178:181], v[118:121]
	v_mfma_f32_16x16x32_bf16 v[114:117], v[170:173], v[178:181], v[114:117]
	v_mfma_f32_16x16x32_bf16 v[102:105], v[162:165], v[186:189], v[102:105]
	v_mfma_f32_16x16x32_bf16 v[98:101], v[170:173], v[186:189], v[98:101]
	v_mfma_f32_16x16x32_bf16 v[86:89], v[162:165], v[206:209], v[86:89]
	v_mfma_f32_16x16x32_bf16 v[82:85], v[170:173], v[206:209], v[82:85]
	v_mfma_f32_16x16x32_bf16 v[70:73], v[162:165], v[214:217], v[70:73]
	v_mfma_f32_16x16x32_bf16 v[66:69], v[170:173], v[214:217], v[66:69]
	v_mfma_f32_16x16x32_bf16 v[118:121], v[166:169], v[182:185], v[118:121]
	v_mfma_f32_16x16x32_bf16 v[114:117], v[174:177], v[182:185], v[114:117]
	v_mfma_f32_16x16x32_bf16 v[102:105], v[166:169], v[190:193], v[102:105]
	v_mfma_f32_16x16x32_bf16 v[98:101], v[174:177], v[190:193], v[98:101]
	v_mfma_f32_16x16x32_bf16 v[86:89], v[166:169], v[210:213], v[86:89]
	v_mfma_f32_16x16x32_bf16 v[82:85], v[174:177], v[210:213], v[82:85]
	v_mfma_f32_16x16x32_bf16 v[70:73], v[166:169], v[218:221], v[70:73]
	v_mfma_f32_16x16x32_bf16 v[66:69], v[174:177], v[218:221], v[66:69]
	s_setprio 0
	s_barrier
; #define PG8_STAGE(bufoff, gbase, voff) do { _Pragma("unroll") for (int _i = 0; _i < 2; ++_i) \
;         __builtin_amdgcn_global_load_lds((const unsigned*)((const char*)(gbase) + (voff)[_i]), (PG8_LAS unsigned*)(lds + (bufoff) + ldsw + _i * 8192), 16, 0, 0); } while (0)
; #define PG8_LDA(dst, b, h) do { _Pragma("unroll") for (int m = 0; m < 4; ++m) _Pragma("unroll") for (int k = 0; k < 2; ++k) dst[m][k] = *(const PG8_LAS bf16x8*)(lds + PG8_SA(b, h) + aoff + m * 2048 + k * 1024); } while (0)
; #define PG8_MMA(ai, bj, At, Bt) do { __builtin_amdgcn_s_setprio(1); _Pragma("unroll") for (int m = 0; m < 4; ++m) _Pragma("unroll") for (int n = 0; n < 2; ++n) _Pragma("unroll") for (int k = 0; k < 2; ++k) \
;         acc[ai][bj][m][n] = __builtin_amdgcn_mfma_f32_16x16x32_bf16(Bt[n][k], At[m][k], acc[ai][bj][m][n], 0, 0, 0); __builtin_amdgcn_s_setprio(0); } while (0)
; #define PG8_WAIT_V(n) asm volatile("s_waitcnt vmcnt(" #n ")" ::: "memory")
; #define PG8_WAIT_L(n) asm volatile("s_waitcnt lgkmcnt(" #n ")" ::: "memory")
; #define PG8_BAR __builtin_amdgcn_s_barrier()
; #define PG8_SCHED __builtin_amdgcn_sched_barrier(0)
; template <class Epi, class Sched, bool ALIGN_EPI = false, bool SP2 = false>
; __device__ __forceinline__ void gemm_phase(PG8_LAS unsigned char* lds, const Gemm g, const Sched& S, const Epi& E) {
;     ...
;             PG8_LDA(At, 1, 1); PG8_STAGE(PG8_SB(1, 0), b3, voffB); PG8_STAGE(PG8_SB(1, 1), b3 + hstepB, voffB); PG8_STAGE(PG8_SA(1, 0), a3, voffA);
;             PG8_WAIT_V(8); PG8_WAIT_L(0); PG8_BAR; PG8_MMA(1, 0, At, B0); PG8_MMA(1, 1, At, B1); PG8_BAR; PG8_SCHED;
	s_add_i32 s22, s43, s25
	v_lshl_add_u64 v[222:223], v[222:223], 0, s[78:79]
	s_mov_b32 m0, s22
	ds_read_b128 v[178:181], v148 offset:49152
	ds_read_b128 v[182:185], v148 offset:50176
	ds_read_b128 v[186:189], v148 offset:51200
	ds_read_b128 v[190:193], v148 offset:52224
	ds_read_b128 v[206:209], v148 offset:53248
	ds_read_b128 v[210:213], v148 offset:54272
	ds_read_b128 v[214:217], v148 offset:55296
	ds_read_b128 v[218:221], v148 offset:56320
	global_load_lds_dwordx4 v[222:223], off
	s_add_i32 m0, s22, 0x2000
	s_add_u32 s20, s20, 0x40080
	v_lshl_add_u64 v[222:223], v[224:225], 0, s[78:79]
	s_addc_u32 s21, s21, 0
	s_add_i32 s22, s44, s25
	global_load_lds_dwordx4 v[222:223], off
	v_lshl_add_u64 v[222:223], s[20:21], 0, v[0:1]
	s_mov_b32 m0, s22
	s_nop 0
	global_load_lds_dwordx4 v[222:223], off
	v_lshl_add_u64 v[222:223], s[20:21], 0, v[130:131]
	s_add_i32 m0, s22, 0x2000
	s_nop 0
	global_load_lds_dwordx4 v[222:223], off
	v_lshl_add_u64 v[222:223], s[18:19], 0, v[134:135]
	s_mov_b32 m0, s30
	s_nop 0
	global_load_lds_dwordx4 v[222:223], off
	v_lshl_add_u64 v[222:223], s[18:19], 0, v[132:133]
	s_mov_b32 m0, s31
	s_nop 0
	global_load_lds_dwordx4 v[222:223], off
	s_waitcnt vmcnt(8)
	s_waitcnt lgkmcnt(0)
	s_barrier
	s_setprio 1
	s_waitcnt lgkmcnt(0)
	v_mfma_f32_16x16x32_bf16 v[62:65], v[142:145], v[178:181], v[62:65]
	v_mfma_f32_16x16x32_bf16 v[58:61], v[154:157], v[178:181], v[58:61]
	v_mfma_f32_16x16x32_bf16 v[46:49], v[142:145], v[186:189], v[46:49]
	v_mfma_f32_16x16x32_bf16 v[42:45], v[154:157], v[186:189], v[42:45]
	v_mfma_f32_16x16x32_bf16 v[30:33], v[142:145], v[206:209], v[30:33]
	v_mfma_f32_16x16x32_bf16 v[26:29], v[154:157], v[206:209], v[26:29]
	v_mfma_f32_16x16x32_bf16 v[14:17], v[142:145], v[214:217], v[14:17]
	v_mfma_f32_16x16x32_bf16 v[10:13], v[154:157], v[214:217], v[10:13]
	v_mfma_f32_16x16x32_bf16 v[62:65], v[150:153], v[182:185], v[62:65]
	v_mfma_f32_16x16x32_bf16 v[58:61], v[158:161], v[182:185], v[58:61]
	v_mfma_f32_16x16x32_bf16 v[46:49], v[150:153], v[190:193], v[46:49]
	v_mfma_f32_16x16x32_bf16 v[42:45], v[158:161], v[190:193], v[42:45]
	v_mfma_f32_16x16x32_bf16 v[30:33], v[150:153], v[210:213], v[30:33]
	v_mfma_f32_16x16x32_bf16 v[26:29], v[158:161], v[210:213], v[26:29]
	v_mfma_f32_16x16x32_bf16 v[14:17], v[150:153], v[218:221], v[14:17]
	v_mfma_f32_16x16x32_bf16 v[10:13], v[158:161], v[218:221], v[10:13]
	s_setprio 0
	s_setprio 1
	v_mfma_f32_16x16x32_bf16 v[54:57], v[162:165], v[178:181], v[54:57]
	v_mfma_f32_16x16x32_bf16 v[50:53], v[170:173], v[178:181], v[50:53]
	v_mfma_f32_16x16x32_bf16 v[38:41], v[162:165], v[186:189], v[38:41]
	v_mfma_f32_16x16x32_bf16 v[34:37], v[170:173], v[186:189], v[34:37]
	v_mfma_f32_16x16x32_bf16 v[22:25], v[162:165], v[206:209], v[22:25]
	v_mfma_f32_16x16x32_bf16 v[18:21], v[170:173], v[206:209], v[18:21]
	v_mfma_f32_16x16x32_bf16 v[6:9], v[162:165], v[214:217], v[6:9]
	v_mfma_f32_16x16x32_bf16 v[2:5], v[170:173], v[214:217], v[2:5]
	v_mfma_f32_16x16x32_bf16 v[54:57], v[166:169], v[182:185], v[54:57]
	v_mfma_f32_16x16x32_bf16 v[50:53], v[174:177], v[182:185], v[50:53]
	v_mfma_f32_16x16x32_bf16 v[38:41], v[166:169], v[190:193], v[38:41]
	v_mfma_f32_16x16x32_bf16 v[34:37], v[174:177], v[190:193], v[34:37]
	v_mfma_f32_16x16x32_bf16 v[22:25], v[166:169], v[210:213], v[22:25]
	v_mfma_f32_16x16x32_bf16 v[18:21], v[174:177], v[210:213], v[18:21]
	v_mfma_f32_16x16x32_bf16 v[6:9], v[166:169], v[218:221], v[6:9]
	v_mfma_f32_16x16x32_bf16 v[2:5], v[174:177], v[218:221], v[2:5]
	s_setprio 0
	s_barrier
	s_add_i32 s42, s42, 2
	s_add_u32 s40, s40, 0x100
	s_addc_u32 s41, s41, 0
	s_add_u32 s16, s16, 0x800000
	s_addc_u32 s17, s17, 0

; #define PG8_STAGE(bufoff, gbase, voff) do { _Pragma("unroll") for (int _i = 0; _i < 2; ++_i) \
;         __builtin_amdgcn_global_load_lds((const unsigned*)((const char*)(gbase) + (voff)[_i]), (PG8_LAS unsigned*)(lds + (bufoff) + ldsw + _i * 8192), 16, 0, 0); } while (0)
; #define PG8_LDA(dst, b, h) do { _Pragma("unroll") for (int m = 0; m < 4; ++m) _Pragma("unroll") for (int k = 0; k < 2; ++k) dst[m][k] = *(const PG8_LAS bf16x8*)(lds + PG8_SA(b, h) + aoff + m * 2048 + k * 1024); } while (0)
; #define PG8_LDB(dst, b, h) do { _Pragma("unroll") for (int n = 0; n < 2; ++n) _Pragma("unroll") for (int k = 0; k < 2; ++k) dst[n][k] = *(const PG8_LAS bf16x8*)(lds + PG8_SB(b, h) + boff + n * 2048 + k * 1024); } while (0)
; #define PG8_MMA(ai, bj, At, Bt) do { __builtin_amdgcn_s_setprio(1); _Pragma("unroll") for (int m = 0; m < 4; ++m) _Pragma("unroll") for (int n = 0; n < 2; ++n) _Pragma("unroll") for (int k = 0; k < 2; ++k) \
;         acc[ai][bj][m][n] = __builtin_amdgcn_mfma_f32_16x16x32_bf16(Bt[n][k], At[m][k], acc[ai][bj][m][n], 0, 0, 0); __builtin_amdgcn_s_setprio(0); } while (0)
; template <class Epi, class Sched, bool ALIGN_EPI = false, bool SP2 = false>
; __device__ __forceinline__ void gemm_phase(PG8_LAS unsigned char* lds, const Gemm g, const Sched& S, const Epi& E) {
;     ...
;         const bool has_next = S.next(ui + 1, nxt);
;         const char* nA = has_next ? (const char*)g.A + (size_t)nxt.pm * tstepA + (size_t)nxt.pn * pnoffA : cA; const char* nB = has_next ? (const char*)g.Bt + (size_t)nxt.pn * tstepB : cB;
;         for (int t = 0; t < nt; t += 2) {
;             const bool last = (t == nt - 2);
;             const char* a1 = cA + (size_t)(t + 1) * kstepA;
;             const char* a2 = last ? nA : cA + (size_t)(t + 2) * kstepA; const char* b2 = last ? nB : cB + (size_t)(t + 2) * kstep;
;             const char* a3 = a2 + kstepA; const char* b3 = b2 + kstep;
;             if (last && has_next) S.a_ready(nxt);
;             if constexpr (SP2) {
;             PG8_LDB(B0, 0, 0); PG8_LDB(B1, 0, 1); PG8_SCHED; PG8_LDA(At, 0, 0); PG8_STAGE(PG8_SA(1, 1), a1 + hstepA, voffA);
;             PG8_WAIT_V(8); PG8_WAIT_L(0); PG8_BAR; PG8_MMA(0, 0, At, B0); PG8_MMA(0, 1, At, B1); PG8_BAR; PG8_SCHED;
;             PG8_LDA(At, 0, 1); PG8_STAGE(PG8_SB(0, 0), b2, voffB); PG8_STAGE(PG8_SB(0, 1), b2 + hstepB, voffB); PG8_STAGE(PG8_SA(0, 0), a2, voffA);
.LBB0_86:
	s_ashr_i32 s17, s16, 31
	s_lshl_b64 s[18:19], s[16:17], 15
	s_add_u32 s18, s70, s18
	s_addc_u32 s19, s71, s19
	s_and_b64 s[20:21], s[6:7], exec
	s_cselect_b32 s17, s19, s23
	s_cselect_b32 s42, s18, s22
	s_ashr_i32 s15, s14, 31
	s_lshl_b64 s[20:21], s[14:15], 19
	v_readlane_b32 s26, v253, 55
	v_readlane_b32 s27, v253, 56
	s_add_u32 s20, s26, s20
	s_addc_u32 s21, s27, s21
	s_and_b64 s[26:27], s[6:7], exec
	s_cselect_b32 s15, s21, s25
	s_cselect_b32 s43, s20, s24
	s_add_u32 s22, s22, 0x204000
	s_addc_u32 s23, s23, 0
	s_add_u32 s44, s24, 0x100
	s_addc_u32 s45, s25, 0
	s_mov_b32 s46, -2
	s_add_u32 s24, s22, 0x1fc000
	s_addc_u32 s25, s23, 0
	s_cmp_eq_u32 s46, 12
	s_cselect_b32 s28, s42, s24
	s_cselect_b32 s29, s17, s25
	s_cselect_b32 s26, s43, s44
	s_cselect_b32 s27, s15, s45
	s_add_u32 s24, s28, 0x200000
	s_addc_u32 s25, s29, 0
	s_add_i32 s47, 0, 0x10000
	s_add_i32 s50, 0, 0x14000
	v_add_u32_e32 v152, s47, v161
	v_add_u32_e32 v172, s50, v161
	ds_read_b128 v[130:133], v152
	ds_read_b128 v[134:137], v152 offset:1024
	ds_read_b128 v[138:141], v152 offset:2048
	ds_read_b128 v[152:155], v152 offset:3072
	ds_read_b128 v[156:159], v172
	ds_read_b128 v[164:167], v172 offset:1024
	ds_read_b128 v[168:171], v172 offset:2048
	ds_read_b128 v[172:175], v172 offset:3072
	v_lshl_add_u64 v[192:193], s[22:23], 0, v[148:149]
	s_add_i32 m0, s31, 0xc000
	ds_read_b128 v[176:179], v163
	ds_read_b128 v[180:183], v163 offset:1024
	ds_read_b128 v[184:187], v163 offset:2048
	ds_read_b128 v[188:191], v163 offset:3072
	ds_read_b128 v[206:209], v163 offset:4096
	ds_read_b128 v[210:213], v163 offset:5120
	ds_read_b128 v[214:217], v163 offset:6144
	ds_read_b128 v[218:221], v163 offset:7168
	global_load_lds_dwordx4 v[192:193], off
	v_lshl_add_u64 v[192:193], s[22:23], 0, v[150:151]
	s_add_i32 m0, s31, 0xe000
	s_nop 0
	global_load_lds_dwordx4 v[192:193], off
	s_waitcnt vmcnt(8)
	s_waitcnt lgkmcnt(0)
	s_barrier
	s_setprio 1
	s_waitcnt lgkmcnt(0)
	v_mfma_f32_16x16x32_bf16 v[126:129], v[130:133], v[176:179], 0
	v_mfma_f32_16x16x32_bf16 v[122:125], v[138:141], v[176:179], 0
	v_mfma_f32_16x16x32_bf16 v[118:121], v[130:133], v[184:187], 0
	v_mfma_f32_16x16x32_bf16 v[106:109], v[138:141], v[184:187], 0
	v_mfma_f32_16x16x32_bf16 v[102:105], v[130:133], v[206:209], 0
	v_mfma_f32_16x16x32_bf16 v[90:93], v[138:141], v[206:209], 0
	v_mfma_f32_16x16x32_bf16 v[86:89], v[130:133], v[214:217], 0
	v_mfma_f32_16x16x32_bf16 v[74:77], v[138:141], v[214:217], 0
	v_mfma_f32_16x16x32_bf16 v[126:129], v[134:137], v[180:183], v[126:129]
	v_mfma_f32_16x16x32_bf16 v[122:125], v[152:155], v[180:183], v[122:125]
	v_mfma_f32_16x16x32_bf16 v[118:121], v[134:137], v[188:191], v[118:121]
	v_mfma_f32_16x16x32_bf16 v[106:109], v[152:155], v[188:191], v[106:109]
	v_mfma_f32_16x16x32_bf16 v[102:105], v[134:137], v[210:213], v[102:105]
	v_mfma_f32_16x16x32_bf16 v[90:93], v[152:155], v[210:213], v[90:93]
	v_mfma_f32_16x16x32_bf16 v[86:89], v[134:137], v[218:221], v[86:89]
	v_mfma_f32_16x16x32_bf16 v[74:77], v[152:155], v[218:221], v[74:77]
	s_setprio 0
	s_setprio 1
	v_mfma_f32_16x16x32_bf16 v[114:117], v[156:159], v[176:179], 0
	v_mfma_f32_16x16x32_bf16 v[110:113], v[168:171], v[176:179], 0
	v_mfma_f32_16x16x32_bf16 v[98:101], v[156:159], v[184:187], 0
	v_mfma_f32_16x16x32_bf16 v[94:97], v[168:171], v[184:187], 0
	v_mfma_f32_16x16x32_bf16 v[82:85], v[156:159], v[206:209], 0
	v_mfma_f32_16x16x32_bf16 v[78:81], v[168:171], v[206:209], 0
	v_mfma_f32_16x16x32_bf16 v[70:73], v[156:159], v[214:217], 0
	v_mfma_f32_16x16x32_bf16 v[66:69], v[168:171], v[214:217], 0
	v_mfma_f32_16x16x32_bf16 v[114:117], v[164:167], v[180:183], v[114:117]
	v_mfma_f32_16x16x32_bf16 v[110:113], v[172:175], v[180:183], v[110:113]
	v_mfma_f32_16x16x32_bf16 v[98:101], v[164:167], v[188:191], v[98:101]
	v_mfma_f32_16x16x32_bf16 v[94:97], v[172:175], v[188:191], v[94:97]
	v_mfma_f32_16x16x32_bf16 v[82:85], v[164:167], v[210:213], v[82:85]
	v_mfma_f32_16x16x32_bf16 v[78:81], v[172:175], v[210:213], v[78:81]
	v_mfma_f32_16x16x32_bf16 v[70:73], v[164:167], v[218:221], v[70:73]
	v_mfma_f32_16x16x32_bf16 v[66:69], v[172:175], v[218:221], v[66:69]
	s_setprio 0
	s_barrier
	s_add_i32 s47, s47, s30
	v_lshl_add_u64 v[192:193], s[26:27], 0, v[0:1]
	s_mov_b32 m0, s47
	ds_read_b128 v[176:179], v163 offset:16384
	ds_read_b128 v[180:183], v163 offset:17408
	ds_read_b128 v[184:187], v163 offset:18432
	ds_read_b128 v[188:191], v163 offset:19456
	ds_read_b128 v[206:209], v163 offset:20480
	ds_read_b128 v[210:213], v163 offset:21504
	ds_read_b128 v[214:217], v163 offset:22528
	ds_read_b128 v[218:221], v163 offset:23552
	global_load_lds_dwordx4 v[192:193], off
	s_add_i32 m0, s47, 0x2000
	s_add_u32 s48, s26, 0x40000
	v_lshl_add_u64 v[222:223], s[26:27], 0, v[142:143]
	s_addc_u32 s49, s27, 0
	s_add_i32 s47, s50, s30
	global_load_lds_dwordx4 v[222:223], off
	v_lshl_add_u64 v[224:225], s[48:49], 0, v[0:1]
	s_mov_b32 m0, s47
	s_nop 0
	global_load_lds_dwordx4 v[224:225], off
	v_lshl_add_u64 v[224:225], s[48:49], 0, v[142:143]
	s_add_i32 m0, s47, 0x2000
	s_nop 0
	global_load_lds_dwordx4 v[224:225], off
	v_lshl_add_u64 v[224:225], s[28:29], 0, v[146:147]
	s_mov_b32 m0, s31
	s_nop 0
	global_load_lds_dwordx4 v[224:225], off
	v_lshl_add_u64 v[224:225], s[28:29], 0, v[144:145]
	s_mov_b32 m0, s34
	s_nop 0
	global_load_lds_dwordx4 v[224:225], off
	s_waitcnt vmcnt(8)
	s_waitcnt lgkmcnt(0)
	s_barrier
; #define PG8_STAGE(bufoff, gbase, voff) do { _Pragma("unroll") for (int _i = 0; _i < 2; ++_i) \
;         __builtin_amdgcn_global_load_lds((const unsigned*)((const char*)(gbase) + (voff)[_i]), (PG8_LAS unsigned*)(lds + (bufoff) + ldsw + _i * 8192), 16, 0, 0); } while (0)
; #define PG8_LDA(dst, b, h) do { _Pragma("unroll") for (int m = 0; m < 4; ++m) _Pragma("unroll") for (int k = 0; k < 2; ++k) dst[m][k] = *(const PG8_LAS bf16x8*)(lds + PG8_SA(b, h) + aoff + m * 2048 + k * 1024); } while (0)
; #define PG8_LDB(dst, b, h) do { _Pragma("unroll") for (int n = 0; n < 2; ++n) _Pragma("unroll") for (int k = 0; k < 2; ++k) dst[n][k] = *(const PG8_LAS bf16x8*)(lds + PG8_SB(b, h) + boff + n * 2048 + k * 1024); } while (0)
; #define PG8_MMA(ai, bj, At, Bt) do { __builtin_amdgcn_s_setprio(1); _Pragma("unroll") for (int m = 0; m < 4; ++m) _Pragma("unroll") for (int n = 0; n < 2; ++n) _Pragma("unroll") for (int k = 0; k < 2; ++k) \
;         acc[ai][bj][m][n] = __builtin_amdgcn_mfma_f32_16x16x32_bf16(Bt[n][k], At[m][k], acc[ai][bj][m][n], 0, 0, 0); __builtin_amdgcn_s_setprio(0); } while (0)
; #define PG8_WAIT_V(n) asm volatile("s_waitcnt vmcnt(" #n ")" ::: "memory")
; #define PG8_WAIT_L(n) asm volatile("s_waitcnt lgkmcnt(" #n ")" ::: "memory")
; #define PG8_BAR __builtin_amdgcn_s_barrier()
; #define PG8_SCHED __builtin_amdgcn_sched_barrier(0)
; template <class Epi, class Sched, bool ALIGN_EPI = false, bool SP2 = false>
; __device__ __forceinline__ void gemm_phase(PG8_LAS unsigned char* lds, const Gemm g, const Sched& S, const Epi& E) {
;     ...
;             PG8_WAIT_V(8); PG8_WAIT_L(0); PG8_BAR; PG8_MMA(1, 0, At, B0); PG8_MMA(1, 1, At, B1); PG8_BAR; PG8_SCHED;
;             PG8_LDB(B0, 1, 0); PG8_LDB(B1, 1, 1); PG8_SCHED; PG8_LDA(At, 1, 0); PG8_STAGE(PG8_SA(0, 1), a2 + hstepA, voffA);
;             PG8_WAIT_V(8); PG8_WAIT_L(0); PG8_BAR; PG8_MMA(0, 0, At, B0); PG8_MMA(0, 1, At, B1); PG8_BAR; PG8_SCHED;
;             PG8_LDA(At, 1, 1); PG8_STAGE(PG8_SB(1, 0), b3, voffB); PG8_STAGE(PG8_SB(1, 1), b3 + hstepB, voffB); PG8_STAGE(PG8_SA(1, 0), a3, voffA);
	s_setprio 1
	s_waitcnt lgkmcnt(0)
	v_mfma_f32_16x16x32_bf16 v[62:65], v[130:133], v[176:179], 0
	v_mfma_f32_16x16x32_bf16 v[58:61], v[138:141], v[176:179], 0
	v_mfma_f32_16x16x32_bf16 v[54:57], v[130:133], v[184:187], 0
	v_mfma_f32_16x16x32_bf16 v[42:45], v[138:141], v[184:187], 0
	v_mfma_f32_16x16x32_bf16 v[38:41], v[130:133], v[206:209], 0
	v_mfma_f32_16x16x32_bf16 v[26:29], v[138:141], v[206:209], 0
	v_mfma_f32_16x16x32_bf16 v[22:25], v[130:133], v[214:217], 0
	v_mfma_f32_16x16x32_bf16 v[10:13], v[138:141], v[214:217], 0
	v_mfma_f32_16x16x32_bf16 v[62:65], v[134:137], v[180:183], v[62:65]
	v_mfma_f32_16x16x32_bf16 v[58:61], v[152:155], v[180:183], v[58:61]
	v_mfma_f32_16x16x32_bf16 v[54:57], v[134:137], v[188:191], v[54:57]
	v_mfma_f32_16x16x32_bf16 v[42:45], v[152:155], v[188:191], v[42:45]
	v_mfma_f32_16x16x32_bf16 v[38:41], v[134:137], v[210:213], v[38:41]
	v_mfma_f32_16x16x32_bf16 v[26:29], v[152:155], v[210:213], v[26:29]
	v_mfma_f32_16x16x32_bf16 v[22:25], v[134:137], v[218:221], v[22:25]
	v_mfma_f32_16x16x32_bf16 v[10:13], v[152:155], v[218:221], v[10:13]
	s_setprio 0
	s_setprio 1
	v_mfma_f32_16x16x32_bf16 v[50:53], v[156:159], v[176:179], 0
	v_mfma_f32_16x16x32_bf16 v[46:49], v[168:171], v[176:179], 0
	v_mfma_f32_16x16x32_bf16 v[34:37], v[156:159], v[184:187], 0
	v_mfma_f32_16x16x32_bf16 v[30:33], v[168:171], v[184:187], 0
	v_mfma_f32_16x16x32_bf16 v[18:21], v[156:159], v[206:209], 0
	v_mfma_f32_16x16x32_bf16 v[14:17], v[168:171], v[206:209], 0
	v_mfma_f32_16x16x32_bf16 v[6:9], v[156:159], v[214:217], 0
	v_mfma_f32_16x16x32_bf16 v[2:5], v[168:171], v[214:217], 0
	v_mfma_f32_16x16x32_bf16 v[50:53], v[164:167], v[180:183], v[50:53]
	v_mfma_f32_16x16x32_bf16 v[46:49], v[172:175], v[180:183], v[46:49]
	v_mfma_f32_16x16x32_bf16 v[34:37], v[164:167], v[188:191], v[34:37]
	v_mfma_f32_16x16x32_bf16 v[30:33], v[172:175], v[188:191], v[30:33]
	v_mfma_f32_16x16x32_bf16 v[18:21], v[164:167], v[210:213], v[18:21]
	v_mfma_f32_16x16x32_bf16 v[14:17], v[172:175], v[210:213], v[14:17]
	v_mfma_f32_16x16x32_bf16 v[6:9], v[164:167], v[218:221], v[6:9]
	v_mfma_f32_16x16x32_bf16 v[2:5], v[172:175], v[218:221], v[2:5]
	s_setprio 0
	s_barrier
	s_add_i32 s47, 0, 0x18000
	s_add_i32 s48, 0, 0x1c000
	v_add_u32_e32 v152, s47, v161
	v_add_u32_e32 v172, s48, v161
	ds_read_b128 v[130:133], v152
	ds_read_b128 v[134:137], v152 offset:1024
	ds_read_b128 v[138:141], v152 offset:2048
	ds_read_b128 v[152:155], v152 offset:3072
	ds_read_b128 v[156:159], v172
	ds_read_b128 v[164:167], v172 offset:1024
	ds_read_b128 v[168:171], v172 offset:2048
	ds_read_b128 v[172:175], v172 offset:3072
	s_add_u32 s28, s28, 0x4000
	s_addc_u32 s29, s29, 0
	s_mov_b32 m0, s35
	v_lshl_add_u64 v[224:225], s[28:29], 0, v[146:147]
	ds_read_b128 v[176:179], v163 offset:32768
	ds_read_b128 v[180:183], v163 offset:33792
	ds_read_b128 v[184:187], v163 offset:34816
	ds_read_b128 v[188:191], v163 offset:35840
	ds_read_b128 v[206:209], v163 offset:36864
	ds_read_b128 v[210:213], v163 offset:37888
	ds_read_b128 v[214:217], v163 offset:38912
	ds_read_b128 v[218:221], v163 offset:39936
	global_load_lds_dwordx4 v[224:225], off
	v_lshl_add_u64 v[224:225], s[28:29], 0, v[144:145]
	s_mov_b32 m0, s36
	s_nop 0
	global_load_lds_dwordx4 v[224:225], off
	s_waitcnt vmcnt(8)
	s_waitcnt lgkmcnt(0)
	s_barrier
	s_setprio 1
	s_waitcnt lgkmcnt(0)
	v_mfma_f32_16x16x32_bf16 v[126:129], v[130:133], v[176:179], v[126:129]
	v_mfma_f32_16x16x32_bf16 v[122:125], v[138:141], v[176:179], v[122:125]
	v_mfma_f32_16x16x32_bf16 v[118:121], v[130:133], v[184:187], v[118:121]
	v_mfma_f32_16x16x32_bf16 v[106:109], v[138:141], v[184:187], v[106:109]
	v_mfma_f32_16x16x32_bf16 v[102:105], v[130:133], v[206:209], v[102:105]
	v_mfma_f32_16x16x32_bf16 v[90:93], v[138:141], v[206:209], v[90:93]
	v_mfma_f32_16x16x32_bf16 v[86:89], v[130:133], v[214:217], v[86:89]
	v_mfma_f32_16x16x32_bf16 v[74:77], v[138:141], v[214:217], v[74:77]
	v_mfma_f32_16x16x32_bf16 v[126:129], v[134:137], v[180:183], v[126:129]
	v_mfma_f32_16x16x32_bf16 v[122:125], v[152:155], v[180:183], v[122:125]
	v_mfma_f32_16x16x32_bf16 v[118:121], v[134:137], v[188:191], v[118:121]
	v_mfma_f32_16x16x32_bf16 v[106:109], v[152:155], v[188:191], v[106:109]
	v_mfma_f32_16x16x32_bf16 v[102:105], v[134:137], v[210:213], v[102:105]
	v_mfma_f32_16x16x32_bf16 v[90:93], v[152:155], v[210:213], v[90:93]
	v_mfma_f32_16x16x32_bf16 v[86:89], v[134:137], v[218:221], v[86:89]
	v_mfma_f32_16x16x32_bf16 v[74:77], v[152:155], v[218:221], v[74:77]
	s_setprio 0
	s_setprio 1
	v_mfma_f32_16x16x32_bf16 v[114:117], v[156:159], v[176:179], v[114:117]
	v_mfma_f32_16x16x32_bf16 v[110:113], v[168:171], v[176:179], v[110:113]
	v_mfma_f32_16x16x32_bf16 v[98:101], v[156:159], v[184:187], v[98:101]
	v_mfma_f32_16x16x32_bf16 v[94:97], v[168:171], v[184:187], v[94:97]
	v_mfma_f32_16x16x32_bf16 v[82:85], v[156:159], v[206:209], v[82:85]
	v_mfma_f32_16x16x32_bf16 v[78:81], v[168:171], v[206:209], v[78:81]
	v_mfma_f32_16x16x32_bf16 v[70:73], v[156:159], v[214:217], v[70:73]
	v_mfma_f32_16x16x32_bf16 v[66:69], v[168:171], v[214:217], v[66:69]
	v_mfma_f32_16x16x32_bf16 v[114:117], v[164:167], v[180:183], v[114:117]
	v_mfma_f32_16x16x32_bf16 v[110:113], v[172:175], v[180:183], v[110:113]
	v_mfma_f32_16x16x32_bf16 v[98:101], v[164:167], v[188:191], v[98:101]
	v_mfma_f32_16x16x32_bf16 v[94:97], v[172:175], v[188:191], v[94:97]
	v_mfma_f32_16x16x32_bf16 v[82:85], v[164:167], v[210:213], v[82:85]
	v_mfma_f32_16x16x32_bf16 v[78:81], v[172:175], v[210:213], v[78:81]
	v_mfma_f32_16x16x32_bf16 v[70:73], v[164:167], v[218:221], v[70:73]
	v_mfma_f32_16x16x32_bf16 v[66:69], v[172:175], v[218:221], v[66:69]
	s_setprio 0
	s_barrier
; #define PG8_STAGE(bufoff, gbase, voff) do { _Pragma("unroll") for (int _i = 0; _i < 2; ++_i) \
;         __builtin_amdgcn_global_load_lds((const unsigned*)((const char*)(gbase) + (voff)[_i]), (PG8_LAS unsigned*)(lds + (bufoff) + ldsw + _i * 8192), 16, 0, 0); } while (0)
; #define PG8_LDA(dst, b, h) do { _Pragma("unroll") for (int m = 0; m < 4; ++m) _Pragma("unroll") for (int k = 0; k < 2; ++k) dst[m][k] = *(const PG8_LAS bf16x8*)(lds + PG8_SA(b, h) + aoff + m * 2048 + k * 1024); } while (0)
; #define PG8_MMA(ai, bj, At, Bt) do { __builtin_amdgcn_s_setprio(1); _Pragma("unroll") for (int m = 0; m < 4; ++m) _Pragma("unroll") for (int n = 0; n < 2; ++n) _Pragma("unroll") for (int k = 0; k < 2; ++k) \
;         acc[ai][bj][m][n] = __builtin_amdgcn_mfma_f32_16x16x32_bf16(Bt[n][k], At[m][k], acc[ai][bj][m][n], 0, 0, 0); __builtin_amdgcn_s_setprio(0); } while (0)
; #define PG8_WAIT_V(n) asm volatile("s_waitcnt vmcnt(" #n ")" ::: "memory")
; #define PG8_WAIT_L(n) asm volatile("s_waitcnt lgkmcnt(" #n ")" ::: "memory")
; #define PG8_BAR __builtin_amdgcn_s_barrier()
; #define PG8_SCHED __builtin_amdgcn_sched_barrier(0)
; template <class Epi, class Sched, bool ALIGN_EPI = false, bool SP2 = false>
; __device__ __forceinline__ void gemm_phase(PG8_LAS unsigned char* lds, const Gemm g, const Sched& S, const Epi& E) {
;     ...
;             PG8_LDA(At, 1, 1); PG8_STAGE(PG8_SB(1, 0), b3, voffB); PG8_STAGE(PG8_SB(1, 1), b3 + hstepB, voffB); PG8_STAGE(PG8_SA(1, 0), a3, voffA);
;             PG8_WAIT_V(8); PG8_WAIT_L(0); PG8_BAR; PG8_MMA(1, 0, At, B0); PG8_MMA(1, 1, At, B1); PG8_BAR; PG8_SCHED;
	s_add_i32 s28, s47, s30
	v_lshl_add_u64 v[192:193], v[192:193], 0, s[78:79]
	s_mov_b32 m0, s28
	ds_read_b128 v[176:179], v163 offset:49152
	ds_read_b128 v[180:183], v163 offset:50176
	ds_read_b128 v[184:187], v163 offset:51200
	ds_read_b128 v[188:191], v163 offset:52224
	ds_read_b128 v[206:209], v163 offset:53248
	ds_read_b128 v[210:213], v163 offset:54272
	ds_read_b128 v[214:217], v163 offset:55296
	ds_read_b128 v[218:221], v163 offset:56320
	global_load_lds_dwordx4 v[192:193], off
	s_add_i32 m0, s28, 0x2000
	s_add_u32 s26, s26, 0x40080
	v_lshl_add_u64 v[192:193], v[222:223], 0, s[78:79]
	s_addc_u32 s27, s27, 0
	s_add_i32 s28, s48, s30
	global_load_lds_dwordx4 v[192:193], off
	v_lshl_add_u64 v[192:193], s[26:27], 0, v[0:1]
	s_mov_b32 m0, s28
	s_nop 0
	global_load_lds_dwordx4 v[192:193], off
	v_lshl_add_u64 v[192:193], s[26:27], 0, v[142:143]
	s_add_i32 m0, s28, 0x2000
	s_nop 0
	global_load_lds_dwordx4 v[192:193], off
	v_lshl_add_u64 v[192:193], s[24:25], 0, v[146:147]
	s_mov_b32 m0, s37
	s_nop 0
	global_load_lds_dwordx4 v[192:193], off
	v_lshl_add_u64 v[192:193], s[24:25], 0, v[144:145]
	s_mov_b32 m0, s38
	s_nop 0
	global_load_lds_dwordx4 v[192:193], off
	s_waitcnt vmcnt(8)
	s_waitcnt lgkmcnt(0)
	s_barrier
	s_setprio 1
	s_waitcnt lgkmcnt(0)
	v_mfma_f32_16x16x32_bf16 v[62:65], v[130:133], v[176:179], v[62:65]
	v_mfma_f32_16x16x32_bf16 v[58:61], v[138:141], v[176:179], v[58:61]
	v_mfma_f32_16x16x32_bf16 v[54:57], v[130:133], v[184:187], v[54:57]
	v_mfma_f32_16x16x32_bf16 v[42:45], v[138:141], v[184:187], v[42:45]
	v_mfma_f32_16x16x32_bf16 v[38:41], v[130:133], v[206:209], v[38:41]
	v_mfma_f32_16x16x32_bf16 v[26:29], v[138:141], v[206:209], v[26:29]
	v_mfma_f32_16x16x32_bf16 v[22:25], v[130:133], v[214:217], v[22:25]
	v_mfma_f32_16x16x32_bf16 v[10:13], v[138:141], v[214:217], v[10:13]
	v_mfma_f32_16x16x32_bf16 v[62:65], v[134:137], v[180:183], v[62:65]
	v_mfma_f32_16x16x32_bf16 v[58:61], v[152:155], v[180:183], v[58:61]
	v_mfma_f32_16x16x32_bf16 v[54:57], v[134:137], v[188:191], v[54:57]
	v_mfma_f32_16x16x32_bf16 v[42:45], v[152:155], v[188:191], v[42:45]
	v_mfma_f32_16x16x32_bf16 v[38:41], v[134:137], v[210:213], v[38:41]
	v_mfma_f32_16x16x32_bf16 v[26:29], v[152:155], v[210:213], v[26:29]
	v_mfma_f32_16x16x32_bf16 v[22:25], v[134:137], v[218:221], v[22:25]
	v_mfma_f32_16x16x32_bf16 v[10:13], v[152:155], v[218:221], v[10:13]
	s_setprio 0
	s_setprio 1
	v_mfma_f32_16x16x32_bf16 v[50:53], v[156:159], v[176:179], v[50:53]
	v_mfma_f32_16x16x32_bf16 v[46:49], v[168:171], v[176:179], v[46:49]
	v_mfma_f32_16x16x32_bf16 v[34:37], v[156:159], v[184:187], v[34:37]
	v_mfma_f32_16x16x32_bf16 v[30:33], v[168:171], v[184:187], v[30:33]
	v_mfma_f32_16x16x32_bf16 v[18:21], v[156:159], v[206:209], v[18:21]
	v_mfma_f32_16x16x32_bf16 v[14:17], v[168:171], v[206:209], v[14:17]
	v_mfma_f32_16x16x32_bf16 v[6:9], v[156:159], v[214:217], v[6:9]
	v_mfma_f32_16x16x32_bf16 v[2:5], v[168:171], v[214:217], v[2:5]
	v_mfma_f32_16x16x32_bf16 v[50:53], v[164:167], v[180:183], v[50:53]
	v_mfma_f32_16x16x32_bf16 v[46:49], v[172:175], v[180:183], v[46:49]
	v_mfma_f32_16x16x32_bf16 v[34:37], v[164:167], v[188:191], v[34:37]
	v_mfma_f32_16x16x32_bf16 v[30:33], v[172:175], v[188:191], v[30:33]
	v_mfma_f32_16x16x32_bf16 v[18:21], v[164:167], v[210:213], v[18:21]
	v_mfma_f32_16x16x32_bf16 v[14:17], v[172:175], v[210:213], v[14:17]
	v_mfma_f32_16x16x32_bf16 v[6:9], v[164:167], v[218:221], v[6:9]
	v_mfma_f32_16x16x32_bf16 v[2:5], v[172:175], v[218:221], v[2:5]
	s_setprio 0
	s_barrier
	s_add_i32 s46, s46, 2
	s_add_u32 s22, s22, 0x400000
	s_addc_u32 s23, s23, 0
	s_add_u32 s44, s44, 0x100
	s_addc_u32 s45, s45, 0

; #define PG8_STAGE(bufoff, gbase, voff) do { _Pragma("unroll") for (int _i = 0; _i < 2; ++_i) \
;         __builtin_amdgcn_global_load_lds((const unsigned*)((const char*)(gbase) + (voff)[_i]), (PG8_LAS unsigned*)(lds + (bufoff) + ldsw + _i * 8192), 16, 0, 0); } while (0)
; #define PG8_LDA(dst, b, h) do { _Pragma("unroll") for (int m = 0; m < 4; ++m) _Pragma("unroll") for (int k = 0; k < 2; ++k) dst[m][k] = *(const PG8_LAS bf16x8*)(lds + PG8_SA(b, h) + aoff + m * 2048 + k * 1024); } while (0)
; #define PG8_LDB(dst, b, h) do { _Pragma("unroll") for (int n = 0; n < 2; ++n) _Pragma("unroll") for (int k = 0; k < 2; ++k) dst[n][k] = *(const PG8_LAS bf16x8*)(lds + PG8_SB(b, h) + boff + n * 2048 + k * 1024); } while (0)
; #define PG8_MMA(ai, bj, At, Bt) do { __builtin_amdgcn_s_setprio(1); _Pragma("unroll") for (int m = 0; m < 4; ++m) _Pragma("unroll") for (int n = 0; n < 2; ++n) _Pragma("unroll") for (int k = 0; k < 2; ++k) \
;         acc[ai][bj][m][n] = __builtin_amdgcn_mfma_f32_16x16x32_bf16(Bt[n][k], At[m][k], acc[ai][bj][m][n], 0, 0, 0); __builtin_amdgcn_s_setprio(0); } while (0)
; template <class Epi, class Sched, bool ALIGN_EPI = false, bool SP2 = false>
; __device__ __forceinline__ void gemm_phase(PG8_LAS unsigned char* lds, const Gemm g, const Sched& S, const Epi& E) {
;     ...
;         const bool has_next = S.next(ui + 1, nxt);
;         const char* nA = has_next ? (const char*)g.A + (size_t)nxt.pm * tstepA + (size_t)nxt.pn * pnoffA : cA; const char* nB = has_next ? (const char*)g.Bt + (size_t)nxt.pn * tstepB : cB;
;         for (int t = 0; t < nt; t += 2) {
;             const bool last = (t == nt - 2);
;             const char* a1 = cA + (size_t)(t + 1) * kstepA;
;             const char* a2 = last ? nA : cA + (size_t)(t + 2) * kstepA; const char* b2 = last ? nB : cB + (size_t)(t + 2) * kstep;
;             const char* a3 = a2 + kstepA; const char* b3 = b2 + kstep;
;             if (last && has_next) S.a_ready(nxt);
;             if constexpr (SP2) {
;             PG8_LDB(B0, 0, 0); PG8_LDB(B1, 0, 1); PG8_SCHED; PG8_LDA(At, 0, 0); PG8_STAGE(PG8_SA(1, 1), a1 + hstepA, voffA);
;             PG8_WAIT_V(8); PG8_WAIT_L(0); PG8_BAR; PG8_MMA(0, 0, At, B0); PG8_MMA(0, 1, At, B1); PG8_BAR; PG8_SCHED;
;             PG8_LDA(At, 0, 1); PG8_STAGE(PG8_SB(0, 0), b2, voffB); PG8_STAGE(PG8_SB(0, 1), b2 + hstepB, voffB); PG8_STAGE(PG8_SA(0, 0), a2, voffA);
.LBB0_332:
	s_ashr_i32 s13, s12, 31
	s_lshl_b64 s[14:15], s[12:13], 15
	s_add_u32 s14, s72, s14
	s_addc_u32 s15, s73, s15
	s_and_b64 s[16:17], s[4:5], exec
	s_cselect_b32 s13, s15, s7
	s_cselect_b32 s36, s14, s6
	s_ashr_i32 s11, s10, 31
	s_lshl_b64 s[16:17], s[10:11], 19
	v_readlane_b32 s20, v254, 7
	v_readlane_b32 s21, v254, 8
	s_add_u32 s16, s20, s16
	s_addc_u32 s17, s21, s17
	s_and_b64 s[20:21], s[4:5], exec
	s_cselect_b32 s11, s17, s19
	s_cselect_b32 s37, s16, s18
	s_add_u32 s38, s18, 0x100
	s_addc_u32 s39, s19, 0
	s_add_u32 s6, s6, 0x204000
	s_addc_u32 s7, s7, 0
	s_mov_b32 s40, -2
	s_add_u32 s18, s6, 0x1fc000
	s_addc_u32 s19, s7, 0
	s_cmp_eq_u32 s40, 12
	s_cselect_b32 s22, s36, s18
	s_cselect_b32 s23, s13, s19
	s_cselect_b32 s20, s37, s38
	s_cselect_b32 s21, s11, s39
	s_add_u32 s18, s22, 0x200000
	s_addc_u32 s19, s23, 0
	s_add_i32 s41, 0, 0x10000
	v_add_u32_e32 v0, s41, v149
	s_add_i32 s44, 0, 0x14000
	ds_read_b128 v[142:145], v0
	ds_read_b128 v[152:155], v0 offset:1024
	ds_read_b128 v[156:159], v0 offset:2048
	ds_read_b128 v[160:163], v0 offset:3072
	v_add_u32_e32 v0, s44, v149
	ds_read_b128 v[164:167], v0
	ds_read_b128 v[168:171], v0 offset:1024
	ds_read_b128 v[172:175], v0 offset:2048
	ds_read_b128 v[176:179], v0 offset:3072
	v_lshl_add_u64 v[146:147], s[6:7], 0, v[138:139]
	s_add_i32 m0, s25, 0xc000
	ds_read_b128 v[180:183], v151
	ds_read_b128 v[184:187], v151 offset:1024
	ds_read_b128 v[188:191], v151 offset:2048
	ds_read_b128 v[206:209], v151 offset:3072
	ds_read_b128 v[210:213], v151 offset:4096
	ds_read_b128 v[214:217], v151 offset:5120
	ds_read_b128 v[218:221], v151 offset:6144
	ds_read_b128 v[222:225], v151 offset:7168
	global_load_lds_dwordx4 v[146:147], off
	v_lshl_add_u64 v[146:147], s[6:7], 0, v[140:141]
	s_add_i32 m0, s25, 0xe000
	s_nop 0
	global_load_lds_dwordx4 v[146:147], off
	s_waitcnt vmcnt(8)
	s_waitcnt lgkmcnt(0)
	s_barrier
	s_setprio 1
	s_waitcnt lgkmcnt(0)
	v_mfma_f32_16x16x32_bf16 v[126:129], v[142:145], v[180:183], 0
	v_mfma_f32_16x16x32_bf16 v[122:125], v[156:159], v[180:183], 0
	v_mfma_f32_16x16x32_bf16 v[110:113], v[142:145], v[188:191], 0
	v_mfma_f32_16x16x32_bf16 v[106:109], v[156:159], v[188:191], 0
	v_mfma_f32_16x16x32_bf16 v[94:97], v[142:145], v[210:213], 0
	v_mfma_f32_16x16x32_bf16 v[90:93], v[156:159], v[210:213], 0
	v_mfma_f32_16x16x32_bf16 v[78:81], v[142:145], v[218:221], 0
	v_mfma_f32_16x16x32_bf16 v[74:77], v[156:159], v[218:221], 0
	v_mfma_f32_16x16x32_bf16 v[126:129], v[152:155], v[184:187], v[126:129]
	v_mfma_f32_16x16x32_bf16 v[122:125], v[160:163], v[184:187], v[122:125]
	v_mfma_f32_16x16x32_bf16 v[110:113], v[152:155], v[206:209], v[110:113]
	v_mfma_f32_16x16x32_bf16 v[106:109], v[160:163], v[206:209], v[106:109]
	v_mfma_f32_16x16x32_bf16 v[94:97], v[152:155], v[214:217], v[94:97]
	v_mfma_f32_16x16x32_bf16 v[90:93], v[160:163], v[214:217], v[90:93]
	v_mfma_f32_16x16x32_bf16 v[78:81], v[152:155], v[222:225], v[78:81]
	v_mfma_f32_16x16x32_bf16 v[74:77], v[160:163], v[222:225], v[74:77]
	s_setprio 0
	s_setprio 1
	v_mfma_f32_16x16x32_bf16 v[118:121], v[164:167], v[180:183], 0
	v_mfma_f32_16x16x32_bf16 v[114:117], v[172:175], v[180:183], 0
	v_mfma_f32_16x16x32_bf16 v[102:105], v[164:167], v[188:191], 0
	v_mfma_f32_16x16x32_bf16 v[98:101], v[172:175], v[188:191], 0
	v_mfma_f32_16x16x32_bf16 v[86:89], v[164:167], v[210:213], 0
	v_mfma_f32_16x16x32_bf16 v[82:85], v[172:175], v[210:213], 0
	v_mfma_f32_16x16x32_bf16 v[70:73], v[164:167], v[218:221], 0
	v_mfma_f32_16x16x32_bf16 v[66:69], v[172:175], v[218:221], 0
	v_mfma_f32_16x16x32_bf16 v[118:121], v[168:171], v[184:187], v[118:121]
	v_mfma_f32_16x16x32_bf16 v[114:117], v[176:179], v[184:187], v[114:117]
	v_mfma_f32_16x16x32_bf16 v[102:105], v[168:171], v[206:209], v[102:105]
	v_mfma_f32_16x16x32_bf16 v[98:101], v[176:179], v[206:209], v[98:101]
	v_mfma_f32_16x16x32_bf16 v[86:89], v[168:171], v[214:217], v[86:89]
	v_mfma_f32_16x16x32_bf16 v[82:85], v[176:179], v[214:217], v[82:85]
	v_mfma_f32_16x16x32_bf16 v[70:73], v[168:171], v[222:225], v[70:73]
	v_mfma_f32_16x16x32_bf16 v[66:69], v[176:179], v[222:225], v[66:69]
	s_setprio 0
	s_barrier
	s_add_i32 s41, s41, s24
	v_lshl_add_u64 v[146:147], s[20:21], 0, v[134:135]
	s_mov_b32 m0, s41
	ds_read_b128 v[180:183], v151 offset:16384
	ds_read_b128 v[184:187], v151 offset:17408
	ds_read_b128 v[188:191], v151 offset:18432
	ds_read_b128 v[206:209], v151 offset:19456
	ds_read_b128 v[210:213], v151 offset:20480
	ds_read_b128 v[214:217], v151 offset:21504
	ds_read_b128 v[218:221], v151 offset:22528
	ds_read_b128 v[222:225], v151 offset:23552
	global_load_lds_dwordx4 v[146:147], off
	s_add_i32 m0, s41, 0x2000
	s_add_u32 s42, s20, 0x40000
	v_lshl_add_u64 v[192:193], s[20:21], 0, v[130:131]
	s_addc_u32 s43, s21, 0
	s_add_i32 s41, s44, s24
	global_load_lds_dwordx4 v[192:193], off
	v_lshl_add_u64 v[226:227], s[42:43], 0, v[134:135]
	s_mov_b32 m0, s41
	s_nop 0
	global_load_lds_dwordx4 v[226:227], off
	v_lshl_add_u64 v[226:227], s[42:43], 0, v[130:131]
	s_add_i32 m0, s41, 0x2000
	s_nop 0
	global_load_lds_dwordx4 v[226:227], off
	v_lshl_add_u64 v[226:227], s[22:23], 0, v[136:137]
	s_mov_b32 m0, s25
	s_nop 0
	global_load_lds_dwordx4 v[226:227], off
	v_lshl_add_u64 v[226:227], s[22:23], 0, v[132:133]
	s_mov_b32 m0, s26
	s_nop 0
	global_load_lds_dwordx4 v[226:227], off
	s_waitcnt vmcnt(8)
	s_waitcnt lgkmcnt(0)
	s_barrier
; #define PG8_STAGE(bufoff, gbase, voff) do { _Pragma("unroll") for (int _i = 0; _i < 2; ++_i) \
;         __builtin_amdgcn_global_load_lds((const unsigned*)((const char*)(gbase) + (voff)[_i]), (PG8_LAS unsigned*)(lds + (bufoff) + ldsw + _i * 8192), 16, 0, 0); } while (0)
; #define PG8_LDA(dst, b, h) do { _Pragma("unroll") for (int m = 0; m < 4; ++m) _Pragma("unroll") for (int k = 0; k < 2; ++k) dst[m][k] = *(const PG8_LAS bf16x8*)(lds + PG8_SA(b, h) + aoff + m * 2048 + k * 1024); } while (0)
; #define PG8_LDB(dst, b, h) do { _Pragma("unroll") for (int n = 0; n < 2; ++n) _Pragma("unroll") for (int k = 0; k < 2; ++k) dst[n][k] = *(const PG8_LAS bf16x8*)(lds + PG8_SB(b, h) + boff + n * 2048 + k * 1024); } while (0)
; #define PG8_MMA(ai, bj, At, Bt) do { __builtin_amdgcn_s_setprio(1); _Pragma("unroll") for (int m = 0; m < 4; ++m) _Pragma("unroll") for (int n = 0; n < 2; ++n) _Pragma("unroll") for (int k = 0; k < 2; ++k) \
;         acc[ai][bj][m][n] = __builtin_amdgcn_mfma_f32_16x16x32_bf16(Bt[n][k], At[m][k], acc[ai][bj][m][n], 0, 0, 0); __builtin_amdgcn_s_setprio(0); } while (0)
; #define PG8_WAIT_V(n) asm volatile("s_waitcnt vmcnt(" #n ")" ::: "memory")
; #define PG8_WAIT_L(n) asm volatile("s_waitcnt lgkmcnt(" #n ")" ::: "memory")
; #define PG8_BAR __builtin_amdgcn_s_barrier()
; #define PG8_SCHED __builtin_amdgcn_sched_barrier(0)
; template <class Epi, class Sched, bool ALIGN_EPI = false, bool SP2 = false>
; __device__ __forceinline__ void gemm_phase(PG8_LAS unsigned char* lds, const Gemm g, const Sched& S, const Epi& E) {
;     ...
;             PG8_WAIT_V(8); PG8_WAIT_L(0); PG8_BAR; PG8_MMA(1, 0, At, B0); PG8_MMA(1, 1, At, B1); PG8_BAR; PG8_SCHED;
;             PG8_LDB(B0, 1, 0); PG8_LDB(B1, 1, 1); PG8_SCHED; PG8_LDA(At, 1, 0); PG8_STAGE(PG8_SA(0, 1), a2 + hstepA, voffA);
;             PG8_WAIT_V(8); PG8_WAIT_L(0); PG8_BAR; PG8_MMA(0, 0, At, B0); PG8_MMA(0, 1, At, B1); PG8_BAR; PG8_SCHED;
;             PG8_LDA(At, 1, 1); PG8_STAGE(PG8_SB(1, 0), b3, voffB); PG8_STAGE(PG8_SB(1, 1), b3 + hstepB, voffB); PG8_STAGE(PG8_SA(1, 0), a3, voffA);
	s_setprio 1
	s_waitcnt lgkmcnt(0)
	v_mfma_f32_16x16x32_bf16 v[62:65], v[142:145], v[180:183], 0
	v_mfma_f32_16x16x32_bf16 v[58:61], v[156:159], v[180:183], 0
	v_mfma_f32_16x16x32_bf16 v[46:49], v[142:145], v[188:191], 0
	v_mfma_f32_16x16x32_bf16 v[42:45], v[156:159], v[188:191], 0
	v_mfma_f32_16x16x32_bf16 v[30:33], v[142:145], v[210:213], 0
	v_mfma_f32_16x16x32_bf16 v[26:29], v[156:159], v[210:213], 0
	v_mfma_f32_16x16x32_bf16 v[14:17], v[142:145], v[218:221], 0
	v_mfma_f32_16x16x32_bf16 v[10:13], v[156:159], v[218:221], 0
	v_mfma_f32_16x16x32_bf16 v[62:65], v[152:155], v[184:187], v[62:65]
	v_mfma_f32_16x16x32_bf16 v[58:61], v[160:163], v[184:187], v[58:61]
	v_mfma_f32_16x16x32_bf16 v[46:49], v[152:155], v[206:209], v[46:49]
	v_mfma_f32_16x16x32_bf16 v[42:45], v[160:163], v[206:209], v[42:45]
	v_mfma_f32_16x16x32_bf16 v[30:33], v[152:155], v[214:217], v[30:33]
	v_mfma_f32_16x16x32_bf16 v[26:29], v[160:163], v[214:217], v[26:29]
	v_mfma_f32_16x16x32_bf16 v[14:17], v[152:155], v[222:225], v[14:17]
	v_mfma_f32_16x16x32_bf16 v[10:13], v[160:163], v[222:225], v[10:13]
	s_setprio 0
	s_setprio 1
	v_mfma_f32_16x16x32_bf16 v[54:57], v[164:167], v[180:183], 0
	v_mfma_f32_16x16x32_bf16 v[50:53], v[172:175], v[180:183], 0
	v_mfma_f32_16x16x32_bf16 v[38:41], v[164:167], v[188:191], 0
	v_mfma_f32_16x16x32_bf16 v[34:37], v[172:175], v[188:191], 0
	v_mfma_f32_16x16x32_bf16 v[22:25], v[164:167], v[210:213], 0
	v_mfma_f32_16x16x32_bf16 v[18:21], v[172:175], v[210:213], 0
	v_mfma_f32_16x16x32_bf16 v[6:9], v[164:167], v[218:221], 0
	v_mfma_f32_16x16x32_bf16 v[2:5], v[172:175], v[218:221], 0
	v_mfma_f32_16x16x32_bf16 v[54:57], v[168:171], v[184:187], v[54:57]
	v_mfma_f32_16x16x32_bf16 v[50:53], v[176:179], v[184:187], v[50:53]
	v_mfma_f32_16x16x32_bf16 v[38:41], v[168:171], v[206:209], v[38:41]
	v_mfma_f32_16x16x32_bf16 v[34:37], v[176:179], v[206:209], v[34:37]
	v_mfma_f32_16x16x32_bf16 v[22:25], v[168:171], v[214:217], v[22:25]
	v_mfma_f32_16x16x32_bf16 v[18:21], v[176:179], v[214:217], v[18:21]
	v_mfma_f32_16x16x32_bf16 v[6:9], v[168:171], v[222:225], v[6:9]
	v_mfma_f32_16x16x32_bf16 v[2:5], v[176:179], v[222:225], v[2:5]
	s_setprio 0
	s_barrier
	s_add_i32 s41, 0, 0x18000
	v_add_u32_e32 v0, s41, v149
	s_add_i32 s42, 0, 0x1c000
	ds_read_b128 v[142:145], v0
	ds_read_b128 v[152:155], v0 offset:1024
	ds_read_b128 v[156:159], v0 offset:2048
	ds_read_b128 v[160:163], v0 offset:3072
	v_add_u32_e32 v0, s42, v149
	ds_read_b128 v[164:167], v0
	ds_read_b128 v[168:171], v0 offset:1024
	ds_read_b128 v[172:175], v0 offset:2048
	ds_read_b128 v[176:179], v0 offset:3072
	s_add_u32 s22, s22, 0x4000
	s_addc_u32 s23, s23, 0
	s_mov_b32 m0, s27
	v_lshl_add_u64 v[226:227], s[22:23], 0, v[136:137]
	ds_read_b128 v[180:183], v151 offset:32768
	ds_read_b128 v[184:187], v151 offset:33792
	ds_read_b128 v[188:191], v151 offset:34816
	ds_read_b128 v[206:209], v151 offset:35840
	ds_read_b128 v[210:213], v151 offset:36864
	ds_read_b128 v[214:217], v151 offset:37888
	ds_read_b128 v[218:221], v151 offset:38912
	ds_read_b128 v[222:225], v151 offset:39936
	global_load_lds_dwordx4 v[226:227], off
	v_lshl_add_u64 v[226:227], s[22:23], 0, v[132:133]
	s_mov_b32 m0, s28
	s_nop 0
	global_load_lds_dwordx4 v[226:227], off
	s_waitcnt vmcnt(8)
	s_waitcnt lgkmcnt(0)
	s_barrier
	s_setprio 1
	s_waitcnt lgkmcnt(0)
	v_mfma_f32_16x16x32_bf16 v[126:129], v[142:145], v[180:183], v[126:129]
	v_mfma_f32_16x16x32_bf16 v[122:125], v[156:159], v[180:183], v[122:125]
	v_mfma_f32_16x16x32_bf16 v[110:113], v[142:145], v[188:191], v[110:113]
	v_mfma_f32_16x16x32_bf16 v[106:109], v[156:159], v[188:191], v[106:109]
	v_mfma_f32_16x16x32_bf16 v[94:97], v[142:145], v[210:213], v[94:97]
	v_mfma_f32_16x16x32_bf16 v[90:93], v[156:159], v[210:213], v[90:93]
	v_mfma_f32_16x16x32_bf16 v[78:81], v[142:145], v[218:221], v[78:81]
	v_mfma_f32_16x16x32_bf16 v[74:77], v[156:159], v[218:221], v[74:77]
	v_mfma_f32_16x16x32_bf16 v[126:129], v[152:155], v[184:187], v[126:129]
	v_mfma_f32_16x16x32_bf16 v[122:125], v[160:163], v[184:187], v[122:125]
	v_mfma_f32_16x16x32_bf16 v[110:113], v[152:155], v[206:209], v[110:113]
	v_mfma_f32_16x16x32_bf16 v[106:109], v[160:163], v[206:209], v[106:109]
	v_mfma_f32_16x16x32_bf16 v[94:97], v[152:155], v[214:217], v[94:97]
	v_mfma_f32_16x16x32_bf16 v[90:93], v[160:163], v[214:217], v[90:93]
	v_mfma_f32_16x16x32_bf16 v[78:81], v[152:155], v[222:225], v[78:81]
	v_mfma_f32_16x16x32_bf16 v[74:77], v[160:163], v[222:225], v[74:77]
	s_setprio 0
	s_setprio 1
	v_mfma_f32_16x16x32_bf16 v[118:121], v[164:167], v[180:183], v[118:121]
	v_mfma_f32_16x16x32_bf16 v[114:117], v[172:175], v[180:183], v[114:117]
	v_mfma_f32_16x16x32_bf16 v[102:105], v[164:167], v[188:191], v[102:105]
	v_mfma_f32_16x16x32_bf16 v[98:101], v[172:175], v[188:191], v[98:101]
	v_mfma_f32_16x16x32_bf16 v[86:89], v[164:167], v[210:213], v[86:89]
	v_mfma_f32_16x16x32_bf16 v[82:85], v[172:175], v[210:213], v[82:85]
	v_mfma_f32_16x16x32_bf16 v[70:73], v[164:167], v[218:221], v[70:73]
	v_mfma_f32_16x16x32_bf16 v[66:69], v[172:175], v[218:221], v[66:69]
	v_mfma_f32_16x16x32_bf16 v[118:121], v[168:171], v[184:187], v[118:121]
	v_mfma_f32_16x16x32_bf16 v[114:117], v[176:179], v[184:187], v[114:117]
	v_mfma_f32_16x16x32_bf16 v[102:105], v[168:171], v[206:209], v[102:105]
	v_mfma_f32_16x16x32_bf16 v[98:101], v[176:179], v[206:209], v[98:101]
	v_mfma_f32_16x16x32_bf16 v[86:89], v[168:171], v[214:217], v[86:89]
	v_mfma_f32_16x16x32_bf16 v[82:85], v[176:179], v[214:217], v[82:85]
	v_mfma_f32_16x16x32_bf16 v[70:73], v[168:171], v[222:225], v[70:73]
	v_mfma_f32_16x16x32_bf16 v[66:69], v[176:179], v[222:225], v[66:69]
	s_setprio 0
	s_barrier
; #define PG8_STAGE(bufoff, gbase, voff) do { _Pragma("unroll") for (int _i = 0; _i < 2; ++_i) \
;         __builtin_amdgcn_global_load_lds((const unsigned*)((const char*)(gbase) + (voff)[_i]), (PG8_LAS unsigned*)(lds + (bufoff) + ldsw + _i * 8192), 16, 0, 0); } while (0)
; #define PG8_LDA(dst, b, h) do { _Pragma("unroll") for (int m = 0; m < 4; ++m) _Pragma("unroll") for (int k = 0; k < 2; ++k) dst[m][k] = *(const PG8_LAS bf16x8*)(lds + PG8_SA(b, h) + aoff + m * 2048 + k * 1024); } while (0)
; #define PG8_MMA(ai, bj, At, Bt) do { __builtin_amdgcn_s_setprio(1); _Pragma("unroll") for (int m = 0; m < 4; ++m) _Pragma("unroll") for (int n = 0; n < 2; ++n) _Pragma("unroll") for (int k = 0; k < 2; ++k) \
;         acc[ai][bj][m][n] = __builtin_amdgcn_mfma_f32_16x16x32_bf16(Bt[n][k], At[m][k], acc[ai][bj][m][n], 0, 0, 0); __builtin_amdgcn_s_setprio(0); } while (0)
; #define PG8_WAIT_V(n) asm volatile("s_waitcnt vmcnt(" #n ")" ::: "memory")
; #define PG8_WAIT_L(n) asm volatile("s_waitcnt lgkmcnt(" #n ")" ::: "memory")
; #define PG8_BAR __builtin_amdgcn_s_barrier()
; #define PG8_SCHED __builtin_amdgcn_sched_barrier(0)
; template <class Epi, class Sched, bool ALIGN_EPI = false, bool SP2 = false>
; __device__ __forceinline__ void gemm_phase(PG8_LAS unsigned char* lds, const Gemm g, const Sched& S, const Epi& E) {
;     ...
;             PG8_LDA(At, 1, 1); PG8_STAGE(PG8_SB(1, 0), b3, voffB); PG8_STAGE(PG8_SB(1, 1), b3 + hstepB, voffB); PG8_STAGE(PG8_SA(1, 0), a3, voffA);
;             PG8_WAIT_V(8); PG8_WAIT_L(0); PG8_BAR; PG8_MMA(1, 0, At, B0); PG8_MMA(1, 1, At, B1); PG8_BAR; PG8_SCHED;
	s_add_i32 s22, s41, s24
	v_lshl_add_u64 v[146:147], v[146:147], 0, s[78:79]
	s_mov_b32 m0, s22
	ds_read_b128 v[180:183], v151 offset:49152
	ds_read_b128 v[184:187], v151 offset:50176
	ds_read_b128 v[188:191], v151 offset:51200
	ds_read_b128 v[206:209], v151 offset:52224
	ds_read_b128 v[210:213], v151 offset:53248
	ds_read_b128 v[214:217], v151 offset:54272
	ds_read_b128 v[218:221], v151 offset:55296
	ds_read_b128 v[222:225], v151 offset:56320
	global_load_lds_dwordx4 v[146:147], off
	s_add_i32 m0, s22, 0x2000
	s_add_u32 s20, s20, 0x40080
	v_lshl_add_u64 v[146:147], v[192:193], 0, s[78:79]
	s_addc_u32 s21, s21, 0
	s_add_i32 s22, s42, s24
	global_load_lds_dwordx4 v[146:147], off
	v_lshl_add_u64 v[146:147], s[20:21], 0, v[134:135]
	s_mov_b32 m0, s22
	s_nop 0
	global_load_lds_dwordx4 v[146:147], off
	v_lshl_add_u64 v[146:147], s[20:21], 0, v[130:131]
	s_add_i32 m0, s22, 0x2000
	s_nop 0
	global_load_lds_dwordx4 v[146:147], off
	v_lshl_add_u64 v[146:147], s[18:19], 0, v[136:137]
	s_mov_b32 m0, s29
	s_nop 0
	global_load_lds_dwordx4 v[146:147], off
	v_lshl_add_u64 v[146:147], s[18:19], 0, v[132:133]
	s_mov_b32 m0, s30
	s_nop 0
	global_load_lds_dwordx4 v[146:147], off
	s_waitcnt vmcnt(8)
	s_waitcnt lgkmcnt(0)
	s_barrier
	s_setprio 1
	s_waitcnt lgkmcnt(0)
	v_mfma_f32_16x16x32_bf16 v[62:65], v[142:145], v[180:183], v[62:65]
	v_mfma_f32_16x16x32_bf16 v[58:61], v[156:159], v[180:183], v[58:61]
	v_mfma_f32_16x16x32_bf16 v[46:49], v[142:145], v[188:191], v[46:49]
	v_mfma_f32_16x16x32_bf16 v[42:45], v[156:159], v[188:191], v[42:45]
	v_mfma_f32_16x16x32_bf16 v[30:33], v[142:145], v[210:213], v[30:33]
	v_mfma_f32_16x16x32_bf16 v[26:29], v[156:159], v[210:213], v[26:29]
	v_mfma_f32_16x16x32_bf16 v[14:17], v[142:145], v[218:221], v[14:17]
	v_mfma_f32_16x16x32_bf16 v[10:13], v[156:159], v[218:221], v[10:13]
	v_mfma_f32_16x16x32_bf16 v[62:65], v[152:155], v[184:187], v[62:65]
	v_mfma_f32_16x16x32_bf16 v[58:61], v[160:163], v[184:187], v[58:61]
	v_mfma_f32_16x16x32_bf16 v[46:49], v[152:155], v[206:209], v[46:49]
	v_mfma_f32_16x16x32_bf16 v[42:45], v[160:163], v[206:209], v[42:45]
	v_mfma_f32_16x16x32_bf16 v[30:33], v[152:155], v[214:217], v[30:33]
	v_mfma_f32_16x16x32_bf16 v[26:29], v[160:163], v[214:217], v[26:29]
	v_mfma_f32_16x16x32_bf16 v[14:17], v[152:155], v[222:225], v[14:17]
	v_mfma_f32_16x16x32_bf16 v[10:13], v[160:163], v[222:225], v[10:13]
	s_setprio 0
	s_setprio 1
	v_mfma_f32_16x16x32_bf16 v[54:57], v[164:167], v[180:183], v[54:57]
	v_mfma_f32_16x16x32_bf16 v[50:53], v[172:175], v[180:183], v[50:53]
	v_mfma_f32_16x16x32_bf16 v[38:41], v[164:167], v[188:191], v[38:41]
	v_mfma_f32_16x16x32_bf16 v[34:37], v[172:175], v[188:191], v[34:37]
	v_mfma_f32_16x16x32_bf16 v[22:25], v[164:167], v[210:213], v[22:25]
	v_mfma_f32_16x16x32_bf16 v[18:21], v[172:175], v[210:213], v[18:21]
	v_mfma_f32_16x16x32_bf16 v[6:9], v[164:167], v[218:221], v[6:9]
	v_mfma_f32_16x16x32_bf16 v[2:5], v[172:175], v[218:221], v[2:5]
	v_mfma_f32_16x16x32_bf16 v[54:57], v[168:171], v[184:187], v[54:57]
	v_mfma_f32_16x16x32_bf16 v[50:53], v[176:179], v[184:187], v[50:53]
	v_mfma_f32_16x16x32_bf16 v[38:41], v[168:171], v[206:209], v[38:41]
	v_mfma_f32_16x16x32_bf16 v[34:37], v[176:179], v[206:209], v[34:37]
	v_mfma_f32_16x16x32_bf16 v[22:25], v[168:171], v[214:217], v[22:25]
	v_mfma_f32_16x16x32_bf16 v[18:21], v[176:179], v[214:217], v[18:21]
	v_mfma_f32_16x16x32_bf16 v[6:9], v[168:171], v[222:225], v[6:9]
	v_mfma_f32_16x16x32_bf16 v[2:5], v[176:179], v[222:225], v[2:5]
	s_setprio 0
	s_barrier
	s_add_i32 s40, s40, 2
	s_add_u32 s38, s38, 0x100
	s_addc_u32 s39, s39, 0
	s_add_u32 s6, s6, 0x400000
	s_addc_u32 s7, s7, 0
